# attention: static priority raise moved from the younger wave half to the older half (s_setprio 3 for waves 0-3)
# baseline (speedup 1.0000x reference)
; __device__ __forceinline__ void unpack8bf(const u32x4 w, float* f) { f[0] = bflo(w.x); f[1] = bfhi(w.x); f[2] = bflo(w.y); f[3] = bfhi(w.y); f[4] = bflo(w.z); f[5] = bfhi(w.z); f[6] = bflo(w.w); f[7] = bfhi(w.w); }
; __device__ __forceinline__ unsigned cvtpk(float lo, float hi) { unsigned r; asm volatile("v_cvt_pk_bf16_f32 %0, %1, %2" : "=v"(r) : "v"(lo), "v"(hi)); return r; }
; __device__ __forceinline__ void attn_unit(const bf16_t* __restrict__ Qb, const bf16_t* __restrict__ Kh, const bf16_t* __restrict__ Vh, bf16_t* __restrict__ Ob, int seq, char* lds, const float* rope, int qpos0) {
;     ...
;   const bf16_t* Qw = Qb + (long)(wid * QBLK + r32) * LDQ + hi * 8;
; #pragma unroll
;   for (int d0 = 0; d0 < 6; ++d0) qr[d0] = *reinterpret_cast<const bf16x8*>(Qw + d0 * 16);
; #pragma unroll
;   for (int d0 = 4; d0 < 6; ++d0) {
;     const float* rp = rope + ((size_t)(qpos0 + wid * QBLK + r32) * 16 + (d0 - 4) * 8 + hi * 4) * 2;
;     const f32x4 t0 = *(const f32x4*)rp, t1 = *(const f32x4*)(rp + 4);
;     float f[8]; unpack8bf(*reinterpret_cast<const u32x4*>(&qr[d0]), f);
;     u32x4 w;
;     w.x = cvtpk(f[0] * t0[0] - f[1] * t0[1], f[0] * t0[1] + f[1] * t0[0]);
;     w.y = cvtpk(f[2] * t0[2] - f[3] * t0[3], f[2] * t0[3] + f[3] * t0[2]);
;     w.z = cvtpk(f[4] * t1[0] - f[5] * t1[1], f[4] * t1[1] + f[5] * t1[0]);
;     w.w = cvtpk(f[6] * t1[2] - f[7] * t1[3], f[6] * t1[3] + f[7] * t1[2]);
;     qr[d0] = *reinterpret_cast<bf16x8*>(&w);
;   }
;   const int kr0 = tid / 12, kc0 = (tid % 12) * 8, kr1 = (512 + tid) / 12, kc1 = ((512 + tid) % 12) * 8; const bool k2 = __builtin_amdgcn_readfirstlane(tid) < 256;
;   const int vr = tid >> 3, vc = (tid & 7) * 8, vst = v_st(vr, vc);
;   const int kst0 = KSWZ(kr0, kc0 * 2), kst1 = KSWZ(kr1, kc1 * 2);
;   const int vb0 = (int)(uintptr_t)V_lds + v_rd_base(lane);
;   struct { bf16x8 vs, ks0, ks1; } sr_;
;   const unsigned vo_ = (unsigned)(vr * LDV + vc) * 2u, ko0_ = (unsigned)(kr0 * LDK + kc0) * 2u, ko1_ = (unsigned)(kr1 * LDK + kc1) * 2u;
;     ...
;   static_assert(SHM_V == SHM_K, "one ring offset serves both");
;   f32x16 pA0, pA1, pB0, pB1; float alA, alB; bf16x8 pa0, pa1, pa2, pa3; const int NT = seq / KVBLK;
;   int bp = 0, bc = SHM_K, bn = 2 * SHM_K;
;   if (__builtin_amdgcn_readfirstlane(tid) >= 256) __builtin_amdgcn_s_setprio(1);
.LBB0_654:
	s_or_b32 s8, s6, s3
	v_mov_b32_e32 v56, v167
	s_or_b32 s12, s8, 0x8000
	s_mul_i32 s6, s12, 0x600
	v_and_b32_e32 v138, 31, v56
	v_ashrrev_i32_e32 v0, 1, v56
	v_and_b32_e32 v118, 0xffffffe0, v0
	v_or_b32_e32 v8, s8, v138
	s_add_u32 s6, s20, s6
	v_add_u32_e32 v8, v8, v118
	s_addc_u32 s7, s21, 0
	s_movk_i32 s9, 0xffe0
	v_ashrrev_i32_e32 v9, 31, v8
	v_bfe_u32 v139, v56, 5, 1
	v_bfi_b32 v2, s9, v0, v56
	v_mov_b64_e32 v[0:1], s[6:7]
	v_lshlrev_b64 v[8:9], 7, v[8:9]
	v_mad_i64_i32 v[0:1], s[6:7], v2, s73, v[0:1]
	v_lshlrev_b32_e32 v116, 4, v139
	v_and_b32_e32 v10, 32, v56
	v_mov_b32_e32 v11, v117
	v_lshl_add_u64 v[8:9], s[94:95], 0, v[8:9]
	v_lshl_add_u64 v[4:5], v[0:1], 0, v[116:117]
	v_lshl_add_u64 v[16:17], v[8:9], 0, v[10:11]
	global_load_dwordx4 v[92:95], v[4:5], off
	global_load_dwordx4 v[88:91], v[4:5], off offset:32
	global_load_dwordx4 v[84:87], v[4:5], off offset:64
	global_load_dwordx4 v[80:83], v[4:5], off offset:96
	global_load_dwordx4 v[0:3], v[4:5], off offset:128
	s_nop 0
	global_load_dwordx4 v[4:7], v[4:5], off offset:160
	s_nop 0
	global_load_dwordx4 v[8:11], v[16:17], off offset:16
	global_load_dwordx4 v[12:15], v[16:17], off
	v_readfirstlane_b32 s8, v56
	s_cmpk_lt_i32 s8, 0x100
	s_waitcnt vmcnt(3)
	v_lshlrev_b32_e32 v18, 16, v0
	v_and_b32_e32 v19, 0xffff0000, v0
	s_waitcnt vmcnt(0)
	v_pk_mul_f32 v[20:21], v[12:13], v[18:19]
	v_pk_mul_f32 v[12:13], v[12:13], v[18:19] op_sel:[1,0] op_sel_hi:[0,1]
	v_sub_f32_e32 v0, v20, v21
	v_add_f32_e32 v12, v12, v13
	v_cvt_pk_bf16_f32 v96, v0, v12
	v_lshlrev_b32_e32 v0, 16, v1
	v_and_b32_e32 v1, 0xffff0000, v1
	v_pk_mul_f32 v[12:13], v[14:15], v[0:1]
	v_pk_mul_f32 v[0:1], v[14:15], v[0:1] op_sel:[1,0] op_sel_hi:[0,1]
	v_add_f32_e32 v0, v0, v1
	v_sub_f32_e32 v12, v12, v13
	v_cvt_pk_bf16_f32 v97, v12, v0
	v_lshlrev_b32_e32 v0, 16, v2
	v_and_b32_e32 v1, 0xffff0000, v2
	v_pk_mul_f32 v[12:13], v[8:9], v[0:1]
	v_pk_mul_f32 v[0:1], v[8:9], v[0:1] op_sel:[1,0] op_sel_hi:[0,1]
	v_add_f32_e32 v0, v0, v1
	v_sub_f32_e32 v2, v12, v13
	v_cvt_pk_bf16_f32 v98, v2, v0
	v_lshlrev_b32_e32 v0, 16, v3
	v_and_b32_e32 v1, 0xffff0000, v3
	v_pk_mul_f32 v[2:3], v[10:11], v[0:1]
	v_pk_mul_f32 v[0:1], v[10:11], v[0:1] op_sel:[1,0] op_sel_hi:[0,1]
	v_sub_f32_e32 v2, v2, v3
	v_add_f32_e32 v0, v0, v1
	v_cvt_pk_bf16_f32 v99, v2, v0
	global_load_dwordx4 v[0:3], v[16:17], off offset:80
	global_load_dwordx4 v[8:11], v[16:17], off offset:64
	v_lshlrev_b32_e32 v12, 16, v4
	v_and_b32_e32 v13, 0xffff0000, v4
	s_waitcnt vmcnt(0)
	v_pk_mul_f32 v[14:15], v[8:9], v[12:13]
	s_nop 0
	v_sub_f32_e32 v4, v14, v15
	v_pk_mul_f32 v[8:9], v[8:9], v[12:13] op_sel:[1,0] op_sel_hi:[0,1]
	v_add_f32_e32 v8, v8, v9
	v_cvt_pk_bf16_f32 v100, v4, v8
	v_lshlrev_b32_e32 v4, 16, v5
	v_and_b32_e32 v5, 0xffff0000, v5
	v_pk_mul_f32 v[8:9], v[10:11], v[4:5]
	v_pk_mul_f32 v[4:5], v[10:11], v[4:5] op_sel:[1,0] op_sel_hi:[0,1]
	v_add_f32_e32 v4, v4, v5
	v_sub_f32_e32 v8, v8, v9
	v_cvt_pk_bf16_f32 v101, v8, v4
	v_lshlrev_b32_e32 v4, 16, v6
	v_and_b32_e32 v5, 0xffff0000, v6
	v_pk_mul_f32 v[8:9], v[0:1], v[4:5]
	v_pk_mul_f32 v[0:1], v[0:1], v[4:5] op_sel:[1,0] op_sel_hi:[0,1]
	v_add_f32_e32 v0, v0, v1
	v_sub_f32_e32 v6, v8, v9
	v_cvt_pk_bf16_f32 v102, v6, v0
	v_lshlrev_b32_e32 v0, 16, v7
	v_and_b32_e32 v1, 0xffff0000, v7
	v_pk_mul_f32 v[4:5], v[2:3], v[0:1]
	v_pk_mul_f32 v[0:1], v[2:3], v[0:1] op_sel:[1,0] op_sel_hi:[0,1]
	v_sub_f32_e32 v4, v4, v5
	v_add_f32_e32 v0, v0, v1
	v_cvt_pk_bf16_f32 v103, v4, v0
	s_cbranch_scc0 .LBB0_656
	s_setprio 3

; __device__ __forceinline__ void unpack8bf(const u32x4 w, float* f) { f[0] = bflo(w.x); f[1] = bfhi(w.x); f[2] = bflo(w.y); f[3] = bfhi(w.y); f[4] = bflo(w.z); f[5] = bfhi(w.z); f[6] = bflo(w.w); f[7] = bfhi(w.w); }
; __device__ __forceinline__ unsigned cvtpk(float lo, float hi) { unsigned r; asm volatile("v_cvt_pk_bf16_f32 %0, %1, %2" : "=v"(r) : "v"(lo), "v"(hi)); return r; }
; __device__ __forceinline__ void attn_unit(const bf16_t* __restrict__ Qb, const bf16_t* __restrict__ Kh, const bf16_t* __restrict__ Vh, bf16_t* __restrict__ Ob, int seq, char* lds, const float* rope, int qpos0) {
;     ...
;   const bf16_t* Qw = Qb + (long)(wid * QBLK + r32) * LDQ + hi * 8;
; #pragma unroll
;   for (int d0 = 0; d0 < 6; ++d0) qr[d0] = *reinterpret_cast<const bf16x8*>(Qw + d0 * 16);
; #pragma unroll
;   for (int d0 = 4; d0 < 6; ++d0) {
;     const float* rp = rope + ((size_t)(qpos0 + wid * QBLK + r32) * 16 + (d0 - 4) * 8 + hi * 4) * 2;
;     const f32x4 t0 = *(const f32x4*)rp, t1 = *(const f32x4*)(rp + 4);
;     float f[8]; unpack8bf(*reinterpret_cast<const u32x4*>(&qr[d0]), f);
;     u32x4 w;
;     w.x = cvtpk(f[0] * t0[0] - f[1] * t0[1], f[0] * t0[1] + f[1] * t0[0]);
;     w.y = cvtpk(f[2] * t0[2] - f[3] * t0[3], f[2] * t0[3] + f[3] * t0[2]);
;     w.z = cvtpk(f[4] * t1[0] - f[5] * t1[1], f[4] * t1[1] + f[5] * t1[0]);
;     w.w = cvtpk(f[6] * t1[2] - f[7] * t1[3], f[6] * t1[3] + f[7] * t1[2]);
;     qr[d0] = *reinterpret_cast<bf16x8*>(&w);
;   }
;   const int kr0 = tid / 12, kc0 = (tid % 12) * 8, kr1 = (512 + tid) / 12, kc1 = ((512 + tid) % 12) * 8; const bool k2 = __builtin_amdgcn_readfirstlane(tid) < 256;
;   const int vr = tid >> 3, vc = (tid & 7) * 8, vst = v_st(vr, vc);
;   const int kst0 = KSWZ(kr0, kc0 * 2), kst1 = KSWZ(kr1, kc1 * 2);
;   const int vb0 = (int)(uintptr_t)V_lds + v_rd_base(lane);
;   struct { bf16x8 vs, ks0, ks1; } sr_;
;   const unsigned vo_ = (unsigned)(vr * LDV + vc) * 2u, ko0_ = (unsigned)(kr0 * LDK + kc0) * 2u, ko1_ = (unsigned)(kr1 * LDK + kc1) * 2u;
;     ...
;   static_assert(SHM_V == SHM_K, "one ring offset serves both");
;   f32x16 pA0, pA1, pB0, pB1; float alA, alB; bf16x8 pa0, pa1, pa2, pa3; const int NT = seq / KVBLK;
;   int bp = 0, bc = SHM_K, bn = 2 * SHM_K;
;   if (__builtin_amdgcn_readfirstlane(tid) >= 256) __builtin_amdgcn_s_setprio(1);
.LBB0_701:
	s_or_b32 s6, s79, s16
	v_mov_b32_e32 v56, v167
	s_mul_i32 s0, s6, 0x60
	s_lshl_b64 s[4:5], s[0:1], 1
	v_and_b32_e32 v138, 31, v56
	v_ashrrev_i32_e32 v0, 1, v56
	v_and_b32_e32 v118, 0xffffffe0, v0
	v_or_b32_e32 v8, s3, v138
	s_add_u32 s8, s19, s4
	v_add_u32_e32 v8, v8, v118
	s_addc_u32 s9, s20, s5
	s_movk_i32 s0, 0xffe0
	v_ashrrev_i32_e32 v9, 31, v8
	v_bfe_u32 v139, v56, 5, 1
	v_bfi_b32 v2, s0, v0, v56
	v_mov_b64_e32 v[0:1], s[8:9]
	v_lshlrev_b64 v[8:9], 7, v[8:9]
	v_mad_i64_i32 v[0:1], s[8:9], v2, s17, v[0:1]
	v_lshlrev_b32_e32 v116, 4, v139
	v_and_b32_e32 v10, 32, v56
	v_mov_b32_e32 v11, v117
	v_lshl_add_u64 v[8:9], s[94:95], 0, v[8:9]
	v_lshl_add_u64 v[4:5], v[0:1], 0, v[116:117]
	v_lshl_add_u64 v[16:17], v[8:9], 0, v[10:11]
	global_load_dwordx4 v[92:95], v[4:5], off
	global_load_dwordx4 v[88:91], v[4:5], off offset:32
	global_load_dwordx4 v[84:87], v[4:5], off offset:64
	global_load_dwordx4 v[80:83], v[4:5], off offset:96
	global_load_dwordx4 v[0:3], v[4:5], off offset:128
	s_nop 0
	global_load_dwordx4 v[4:7], v[4:5], off offset:160
	s_nop 0
	global_load_dwordx4 v[8:11], v[16:17], off offset:16
	global_load_dwordx4 v[12:15], v[16:17], off
	v_readfirstlane_b32 s0, v56
	s_cmpk_lt_i32 s0, 0x100
	s_waitcnt vmcnt(3)
	v_lshlrev_b32_e32 v18, 16, v0
	v_and_b32_e32 v19, 0xffff0000, v0
	s_waitcnt vmcnt(0)
	v_pk_mul_f32 v[20:21], v[12:13], v[18:19]
	v_pk_mul_f32 v[12:13], v[12:13], v[18:19] op_sel:[1,0] op_sel_hi:[0,1]
	v_sub_f32_e32 v0, v20, v21
	v_add_f32_e32 v12, v12, v13
	v_cvt_pk_bf16_f32 v96, v0, v12
	v_lshlrev_b32_e32 v0, 16, v1
	v_and_b32_e32 v1, 0xffff0000, v1
	v_pk_mul_f32 v[12:13], v[14:15], v[0:1]
	v_pk_mul_f32 v[0:1], v[14:15], v[0:1] op_sel:[1,0] op_sel_hi:[0,1]
	v_add_f32_e32 v0, v0, v1
	v_sub_f32_e32 v12, v12, v13
	v_cvt_pk_bf16_f32 v97, v12, v0
	v_lshlrev_b32_e32 v0, 16, v2
	v_and_b32_e32 v1, 0xffff0000, v2
	v_pk_mul_f32 v[12:13], v[8:9], v[0:1]
	v_pk_mul_f32 v[0:1], v[8:9], v[0:1] op_sel:[1,0] op_sel_hi:[0,1]
	v_add_f32_e32 v0, v0, v1
	v_sub_f32_e32 v2, v12, v13
	v_cvt_pk_bf16_f32 v98, v2, v0
	v_lshlrev_b32_e32 v0, 16, v3
	v_and_b32_e32 v1, 0xffff0000, v3
	v_pk_mul_f32 v[2:3], v[10:11], v[0:1]
	v_pk_mul_f32 v[0:1], v[10:11], v[0:1] op_sel:[1,0] op_sel_hi:[0,1]
	v_sub_f32_e32 v2, v2, v3
	v_add_f32_e32 v0, v0, v1
	v_cvt_pk_bf16_f32 v99, v2, v0
	global_load_dwordx4 v[0:3], v[16:17], off offset:80
	global_load_dwordx4 v[8:11], v[16:17], off offset:64
	v_lshlrev_b32_e32 v12, 16, v4
	v_and_b32_e32 v13, 0xffff0000, v4
	s_waitcnt vmcnt(0)
	v_pk_mul_f32 v[14:15], v[8:9], v[12:13]
	s_nop 0
	v_sub_f32_e32 v4, v14, v15
	v_pk_mul_f32 v[8:9], v[8:9], v[12:13] op_sel:[1,0] op_sel_hi:[0,1]
	v_add_f32_e32 v8, v8, v9
	v_cvt_pk_bf16_f32 v100, v4, v8
	v_lshlrev_b32_e32 v4, 16, v5
	v_and_b32_e32 v5, 0xffff0000, v5
	v_pk_mul_f32 v[8:9], v[10:11], v[4:5]
	v_pk_mul_f32 v[4:5], v[10:11], v[4:5] op_sel:[1,0] op_sel_hi:[0,1]
	v_add_f32_e32 v4, v4, v5
	v_sub_f32_e32 v8, v8, v9
	v_cvt_pk_bf16_f32 v101, v8, v4
	v_lshlrev_b32_e32 v4, 16, v6
	v_and_b32_e32 v5, 0xffff0000, v6
	v_pk_mul_f32 v[8:9], v[0:1], v[4:5]
	v_pk_mul_f32 v[0:1], v[0:1], v[4:5] op_sel:[1,0] op_sel_hi:[0,1]
	v_add_f32_e32 v0, v0, v1
	v_sub_f32_e32 v6, v8, v9
	v_cvt_pk_bf16_f32 v102, v6, v0
	v_lshlrev_b32_e32 v0, 16, v7
	v_and_b32_e32 v1, 0xffff0000, v7
	v_pk_mul_f32 v[4:5], v[2:3], v[0:1]
	v_pk_mul_f32 v[0:1], v[2:3], v[0:1] op_sel:[1,0] op_sel_hi:[0,1]
	v_sub_f32_e32 v4, v4, v5
	v_add_f32_e32 v0, v0, v1
	v_cvt_pk_bf16_f32 v103, v4, v0
	s_cbranch_scc0 .LBB0_703
	s_setprio 3

; template <int RPL, int NSW>
; __device__ __forceinline__ void scan_item(const P& p, LAS unsigned char* lds, int seqbase, int L, int head, int dir, int part, int step0, int nsteps, int mode, float* qc, float* smid) {
;     ...
;         const int i = lane >> 4, kq = lane & 15, lr0 = wave * (4 * RPL) + i * RPL;
;         static_assert((2 * BUF_FLOATS + 4 * TC * WR) * 4 <= LDS_BYTES - 256, "scan LDS incl. the dummy Y region");
;         const bool yleader = (kq & 3) == 0;
;         f32x2 S[RPL][2];
; #pragma unroll
;         for (int q = 0; q < RPL; ++q) { const int gk = rowbase + lr0 + q - 4 * kq;
;             S[q][0] = (f32x2){(mode && gk == 0) ? 1.f : 0.f, (mode && gk == 1) ? 1.f : 0.f}; S[q][1] = (f32x2){(mode && gk == 2) ? 1.f : 0.f, (mode && gk == 3) ? 1.f : 0.f}; }
;         __syncthreads();
;         for (int ch = 0; ch < NC; ++ch) {
;             LAS const float* b = lf + (ch & 1) * BUF_FLOATS; LAS float* yb = lf + (ch & 1) * BUF_FLOATS + 5 * ARR + TC * WR;
;             LAS float* ywb = (yleader ? yb : lf + 2 * BUF_FLOATS) + lr0 * 4 + (kq >> 2);
;             f32x4 xw, xkd, xkk, xb, xr; float vrow[RPL];
;     ...
;             SCAN_LD(0);
; #pragma unroll 16
;             for (int s = 0; s < TC; ++s) {
;                 const f32x2 w0 = {xw[0], xw[1]}, w1 = {xw[2], xw[3]}, kd0 = {xkd[0], xkd[1]}, kd1 = {xkd[2], xkd[3]}, kk0 = {xkk[0], xkk[1]}, kk1 = {xkk[2], xkk[3]},
;                             b0 = {xb[0], xb[1]}, b1 = {xb[2], xb[3]}, r0 = {xr[0], xr[1]}, r1 = {xr[2], xr[3]};
;                 float vr[RPL];
; #pragma unroll
;                 for (int q = 0; q < RPL; ++q) vr[q] = vrow[q];
;                 { const int sn = (s + 1 < TC) ? s + 1 : s; SCAN_LD(sn); }
;                 float sa[RPL];
; #pragma unroll
;                 for (int q = 0; q < RPL; ++q) { const f32x2 t = S[q][0] * kk0 + S[q][1] * kk1; sa[q] = t.x + t.y; }
;                 if (RPL == 2) {
;                     sa[0] += dppx<0xB1>(sa[0]); sa[RPL - 1] += dppx<0xB1>(sa[RPL - 1]); sa[0] += dppx<0x4E>(sa[0]); sa[RPL - 1] += dppx<0x4E>(sa[RPL - 1]);
;                     sa[0] += dppx<0x141>(sa[0]); sa[RPL - 1] += dppx<0x141>(sa[RPL - 1]); sa[0] += dppx<0x140>(sa[0]); sa[RPL - 1] += dppx<0x140>(sa[RPL - 1]);
;                 } else {
; #pragma unroll
;                     for (int q = 0; q < RPL; ++q) sa[q] = reduce16(sa[q]);
;                 }
;                 float ov[RPL];
.LBB0_973:
	v_mov_b32_e32 v58, v167
	s_and_b32 s1, s35, 1
	s_lshl_b32 s39, s1, 5
	v_readfirstlane_b32 s11, v58
	s_ashr_i32 s7, s11, 6
	s_cmp_lt_i32 s7, 4
	s_mov_b64 s[4:5], -1
	s_cbranch_scc0 .LBB0_981
	v_lshrrev_b32_e32 v1, 3, v58
	v_and_b32_e32 v1, 6, v1
	v_and_b32_e32 v0, 15, v58
	v_lshl_or_b32 v51, s7, 3, v1
	v_add_u32_e32 v48, s39, v51
	v_lshlrev_b32_e32 v49, 2, v0
	s_cmp_lg_u32 s10, 0
	s_cselect_b64 s[24:25], -1, 0
	v_sub_u32_e32 v2, v48, v49
	v_cmp_eq_u32_e32 vcc, v48, v49
	v_or_b32_e32 v50, 1, v48
	s_and_b64 s[26:27], s[24:25], vcc
	v_cmp_eq_u32_e32 vcc, 2, v2
	v_sub_u32_e32 v6, v50, v49
	v_cndmask_b32_e64 v168, 0, 1.0, s[26:27]
	s_and_b64 s[26:27], s[24:25], vcc
	v_cmp_eq_u32_e32 vcc, 1, v6
	v_and_b32_e32 v1, 3, v58
	v_cndmask_b32_e64 v2, 0, 1.0, s[26:27]
	s_and_b64 s[26:27], s[24:25], vcc
	v_cmp_eq_u32_e32 vcc, 3, v6
	s_and_b64 s[24:25], s[24:25], vcc
	v_cmp_eq_u32_e32 vcc, 0, v1
	v_bfe_u32 v1, v58, 4, 2
	s_lshl_b32 s5, s7, 7
	v_lshlrev_b32_e32 v8, 5, v1
	v_and_b32_e32 v9, 12, v58
	v_or3_b32 v59, s5, v8, v9
	s_lshl_b32 s5, s7, 5
	s_add_i32 s5, s5, 0
	s_add_i32 s5, s5, 0xa080
	s_mov_b32 s4, 0
	v_mov_b32_e32 v3, v169
	v_cndmask_b32_e64 v5, 0, 1.0, s[26:27]
	v_mov_b32_e32 v4, v169
	v_cndmask_b32_e64 v7, 0, 1.0, s[24:25]
	v_mov_b32_e32 v6, v169
	v_lshl_add_u32 v60, v1, 3, s5
	v_lshl_add_u32 v61, v0, 4, s3
	v_mov_b64_e32 v[0:1], v[168:169]
	s_barrier
.LBB0_975:
	s_bitcmp1_b32 s4, 0
	s_cselect_b32 s5, 0xf000, 0
	s_add_i32 s7, s5, 0
	s_add_i32 s13, s7, 0xb000
	v_mov_b32_e32 v8, s14
	v_mov_b32_e32 v9, s13
	v_lshl_add_u32 v62, v49, 2, s7
	v_cndmask_b32_e32 v24, v8, v9, vcc
	ds_read_b128 v[16:19], v62 offset:8192
	ds_read_b128 v[44:47], v62 offset:16384
	ds_read_b128 v[12:15], v62
	ds_read_b128 v[8:11], v62 offset:32768
	v_lshl_add_u32 v63, v51, 2, s7
	ds_read_b128 v[20:23], v62 offset:24576
	ds_read_b64 v[52:53], v63 offset:40960
	v_add_u32_e32 v64, v24, v59
	v_add_u32_e32 v65, s5, v60
	v_add_u32_e32 v66, s5, v61
	s_mov_b32 s5, 16
	s_mov_b32 s7, 0
.LBB0_976:
	s_waitcnt lgkmcnt(4)
	v_pk_mul_f32 v[56:57], v[2:3], v[46:47]
	v_pk_mul_f32 v[46:47], v[6:7], v[46:47]
	v_pk_fma_f32 v[68:69], v[0:1], v[44:45], v[56:57]
	v_pk_fma_f32 v[46:47], v[4:5], v[44:45], v[46:47]
	v_add_f32_e32 v69, v68, v69
	v_add_f32_e32 v46, v46, v47
	ds_read_b128 v[32:35], v66 offset:8192
	ds_read_b128 v[40:43], v66 offset:16384
	ds_read_b128 v[36:39], v66 offset:24576
	ds_read_b128 v[28:31], v66
	ds_read_b128 v[24:27], v66 offset:32768
	ds_read_b64 v[54:55], v65
	v_add_f32_dpp v47, v69, v69 quad_perm:[1,0,3,2] row_mask:0xf bank_mask:0xf bound_ctrl:1
	v_add_f32_dpp v46, v46, v46 quad_perm:[1,0,3,2] row_mask:0xf bank_mask:0xf bound_ctrl:1
	v_add_u32_e32 v67, s7, v64
	v_add_f32_dpp v47, v47, v47 quad_perm:[2,3,0,1] row_mask:0xf bank_mask:0xf bound_ctrl:1
	v_add_f32_dpp v46, v46, v46 quad_perm:[2,3,0,1] row_mask:0xf bank_mask:0xf bound_ctrl:1
	v_add_u32_e32 v74, 0x400, v67
	v_add_f32_dpp v47, v47, v47 row_half_mirror row_mask:0xf bank_mask:0xf bound_ctrl:1
	v_add_f32_dpp v69, v46, v46 row_half_mirror row_mask:0xf bank_mask:0xf bound_ctrl:1
	v_add_u32_e32 v75, 0x800, v67
	v_add_f32_dpp v46, v47, v47 row_mirror row_mask:0xf bank_mask:0xf bound_ctrl:1
	v_add_f32_dpp v70, v69, v69 row_mirror row_mask:0xf bank_mask:0xf bound_ctrl:1
	s_waitcnt lgkmcnt(7)
	v_pk_mul_f32 v[72:73], v[20:21], v[46:47] op_sel_hi:[1,0] neg_lo:[0,1] neg_hi:[0,1]
	v_pk_mul_f32 v[20:21], v[20:21], v[70:71] op_sel_hi:[1,0] neg_lo:[0,1] neg_hi:[0,1]
	v_pk_mul_f32 v[46:47], v[22:23], v[46:47] op_sel_hi:[1,0] neg_lo:[0,1] neg_hi:[0,1]
	v_pk_mul_f32 v[22:23], v[22:23], v[70:71] op_sel_hi:[1,0] neg_lo:[0,1] neg_hi:[0,1]
	s_waitcnt lgkmcnt(6)
	v_pk_fma_f32 v[70:71], v[52:53], v[16:17], v[72:73] op_sel_hi:[0,1,1]
	v_pk_fma_f32 v[16:17], v[52:53], v[16:17], v[20:21] op_sel:[1,0,0]
	v_pk_fma_f32 v[20:21], v[52:53], v[18:19], v[46:47] op_sel_hi:[0,1,1]
	v_pk_fma_f32 v[18:19], v[52:53], v[18:19], v[22:23] op_sel:[1,0,0]
	v_pk_fma_f32 v[20:21], v[2:3], v[14:15], v[20:21]
	v_pk_fma_f32 v[52:53], v[6:7], v[14:15], v[18:19]
	v_pk_fma_f32 v[22:23], v[0:1], v[12:13], v[70:71]
	v_pk_fma_f32 v[46:47], v[4:5], v[12:13], v[16:17]
	v_pk_mul_f32 v[0:1], v[10:11], v[20:21]
	v_pk_mul_f32 v[2:3], v[10:11], v[52:53]
	s_waitcnt lgkmcnt(4)
	v_pk_mul_f32 v[4:5], v[20:21], v[42:43]
	v_pk_mul_f32 v[6:7], v[52:53], v[42:43]
	v_pk_fma_f32 v[0:1], v[8:9], v[22:23], v[0:1]
	v_pk_fma_f32 v[2:3], v[8:9], v[46:47], v[2:3]
	v_pk_fma_f32 v[4:5], v[22:23], v[40:41], v[4:5]
	v_pk_fma_f32 v[6:7], v[46:47], v[40:41], v[6:7]
	v_add_f32_e32 v0, v0, v1
	v_add_f32_e32 v1, v2, v3
	v_add_f32_e32 v2, v4, v5
	v_add_f32_e32 v3, v6, v7
	v_add_f32_dpp v0, v0, v0 quad_perm:[1,0,3,2] row_mask:0xf bank_mask:0xf bound_ctrl:1
	v_add_f32_dpp v2, v2, v2 quad_perm:[1,0,3,2] row_mask:0xf bank_mask:0xf bound_ctrl:1
	v_add_f32_dpp v3, v3, v3 quad_perm:[1,0,3,2] row_mask:0xf bank_mask:0xf bound_ctrl:1
	v_add_f32_dpp v1, v1, v1 quad_perm:[1,0,3,2] row_mask:0xf bank_mask:0xf bound_ctrl:1
	v_add_f32_dpp v2, v2, v2 quad_perm:[2,3,0,1] row_mask:0xf bank_mask:0xf bound_ctrl:1
	v_add_f32_dpp v3, v3, v3 quad_perm:[2,3,0,1] row_mask:0xf bank_mask:0xf bound_ctrl:1
	v_add_f32_dpp v0, v0, v0 quad_perm:[2,3,0,1] row_mask:0xf bank_mask:0xf bound_ctrl:1
	v_add_f32_dpp v42, v2, v2 row_half_mirror row_mask:0xf bank_mask:0xf bound_ctrl:1
	v_add_f32_dpp v43, v3, v3 row_half_mirror row_mask:0xf bank_mask:0xf bound_ctrl:1
	v_add_f32_dpp v1, v1, v1 quad_perm:[2,3,0,1] row_mask:0xf bank_mask:0xf bound_ctrl:1
	v_add_f32_dpp v42, v42, v42 row_mirror row_mask:0xf bank_mask:0xf bound_ctrl:1
	v_add_f32_dpp v70, v43, v43 row_mirror row_mask:0xf bank_mask:0xf bound_ctrl:1
	s_waitcnt lgkmcnt(3)
; template <int RPL, int NSW>
; __device__ __forceinline__ void scan_item(const P& p, LAS unsigned char* lds, int seqbase, int L, int head, int dir, int part, int step0, int nsteps, int mode, float* qc, float* smid) {
;     ...
;             for (int s = 0; s < TC; ++s) {
;                 const f32x2 w0 = {xw[0], xw[1]}, w1 = {xw[2], xw[3]}, kd0 = {xkd[0], xkd[1]}, kd1 = {xkd[2], xkd[3]}, kk0 = {xkk[0], xkk[1]}, kk1 = {xkk[2], xkk[3]},
;                             b0 = {xb[0], xb[1]}, b1 = {xb[2], xb[3]}, r0 = {xr[0], xr[1]}, r1 = {xr[2], xr[3]};
;                 float vr[RPL];
; #pragma unroll
;                 for (int q = 0; q < RPL; ++q) vr[q] = vrow[q];
;                 { const int sn = (s + 1 < TC) ? s + 1 : s; SCAN_LD(sn); }
;                 float sa[RPL];
; #pragma unroll
;                 for (int q = 0; q < RPL; ++q) { const f32x2 t = S[q][0] * kk0 + S[q][1] * kk1; sa[q] = t.x + t.y; }
;                 if (RPL == 2) {
;                     sa[0] += dppx<0xB1>(sa[0]); sa[RPL - 1] += dppx<0xB1>(sa[RPL - 1]); sa[0] += dppx<0x4E>(sa[0]); sa[RPL - 1] += dppx<0x4E>(sa[RPL - 1]);
;                     sa[0] += dppx<0x141>(sa[0]); sa[RPL - 1] += dppx<0x141>(sa[RPL - 1]); sa[0] += dppx<0x140>(sa[0]); sa[RPL - 1] += dppx<0x140>(sa[RPL - 1]);
;                 } else {
; #pragma unroll
;                     for (int q = 0; q < RPL; ++q) sa[q] = reduce16(sa[q]);
;                 }
;                 float ov[RPL];
;                 if (RPL == 2) {
;                     const f32x2 vva = {vr[0], vr[0]}, nsa = {-sa[0], -sa[0]}, vvb = {vr[RPL - 1], vr[RPL - 1]}, nsb = {-sa[RPL - 1], -sa[RPL - 1]};
;                     f32x2 a0 = nsa * b0, c0 = nsb * b0, a1 = nsa * b1, c1 = nsb * b1;
;                     a0 = vva * kd0 + a0; c0 = vvb * kd0 + c0; a1 = vva * kd1 + a1; c1 = vvb * kd1 + c1;
;                     S[0][0] = S[0][0] * w0 + a0; S[RPL - 1][0] = S[RPL - 1][0] * w0 + c0; S[0][1] = S[0][1] * w1 + a1; S[RPL - 1][1] = S[RPL - 1][1] * w1 + c1;
;                     f32x2 ua = S[0][0] * r0, ub = S[RPL - 1][0] * r0;
;                     ua = S[0][1] * r1 + ua; ub = S[RPL - 1][1] * r1 + ub;
;                     ov[0] = ua.x + ua.y; ov[RPL - 1] = ub.x + ub.y;
;                 } else {
; #pragma unroll
;                 for (int q = 0; q < RPL; ++q) {
;                     const f32x2 vv = {vr[q], vr[q]}, ns = {-sa[q], -sa[q]};
	v_pk_mul_f32 v[72:73], v[36:37], v[42:43] op_sel_hi:[1,0] neg_lo:[0,1] neg_hi:[0,1]
	v_pk_mul_f32 v[36:37], v[36:37], v[70:71] op_sel_hi:[1,0] neg_lo:[0,1] neg_hi:[0,1]
	v_pk_mul_f32 v[42:43], v[38:39], v[42:43] op_sel_hi:[1,0] neg_lo:[0,1] neg_hi:[0,1]
	v_pk_mul_f32 v[38:39], v[38:39], v[70:71] op_sel_hi:[1,0] neg_lo:[0,1] neg_hi:[0,1]
	s_waitcnt lgkmcnt(0)
	v_pk_fma_f32 v[70:71], v[54:55], v[32:33], v[72:73] op_sel_hi:[0,1,1]
	v_pk_fma_f32 v[32:33], v[54:55], v[32:33], v[36:37] op_sel:[1,0,0]
	v_pk_fma_f32 v[36:37], v[54:55], v[34:35], v[42:43] op_sel_hi:[0,1,1]
	v_pk_fma_f32 v[34:35], v[54:55], v[34:35], v[38:39] op_sel:[1,0,0]
	ds_write2_b32 v67, v0, v1 offset1:4
	v_pk_fma_f32 v[42:43], v[46:47], v[28:29], v[32:33]
	v_pk_fma_f32 v[36:37], v[20:21], v[30:31], v[36:37]
	v_pk_fma_f32 v[46:47], v[52:53], v[30:31], v[34:35]
	ds_read_b128 v[0:3], v66 offset:8448
	ds_read_b128 v[4:7], v66 offset:16640
	ds_read_b128 v[8:11], v66 offset:24832
	ds_read_b128 v[12:15], v66 offset:256
	ds_read_b128 v[16:19], v66 offset:33024
	ds_read_b64 v[40:41], v65 offset:128
	v_pk_fma_f32 v[38:39], v[22:23], v[28:29], v[70:71]
	v_pk_mul_f32 v[20:21], v[26:27], v[36:37]
	v_pk_mul_f32 v[22:23], v[26:27], v[46:47]
	v_pk_fma_f32 v[20:21], v[24:25], v[38:39], v[20:21]
	v_pk_fma_f32 v[22:23], v[24:25], v[42:43], v[22:23]
	s_waitcnt lgkmcnt(4)
	v_pk_mul_f32 v[24:25], v[36:37], v[6:7]
	v_pk_mul_f32 v[6:7], v[46:47], v[6:7]
	v_add_f32_e32 v26, v20, v21
	v_add_f32_e32 v22, v22, v23
	v_pk_fma_f32 v[20:21], v[38:39], v[4:5], v[24:25]
	v_pk_fma_f32 v[4:5], v[42:43], v[4:5], v[6:7]
	v_add_f32_dpp v6, v26, v26 quad_perm:[1,0,3,2] row_mask:0xf bank_mask:0xf bound_ctrl:1
	v_add_f32_dpp v7, v22, v22 quad_perm:[1,0,3,2] row_mask:0xf bank_mask:0xf bound_ctrl:1
	v_add_f32_e32 v20, v20, v21
	v_add_f32_e32 v4, v4, v5
	v_add_f32_dpp v5, v6, v6 quad_perm:[2,3,0,1] row_mask:0xf bank_mask:0xf bound_ctrl:1
	v_add_f32_dpp v6, v7, v7 quad_perm:[2,3,0,1] row_mask:0xf bank_mask:0xf bound_ctrl:1
	v_add_f32_dpp v7, v20, v20 quad_perm:[1,0,3,2] row_mask:0xf bank_mask:0xf bound_ctrl:1
	v_add_f32_dpp v4, v4, v4 quad_perm:[1,0,3,2] row_mask:0xf bank_mask:0xf bound_ctrl:1
	ds_write2_b32 v67, v5, v6 offset0:128 offset1:132
	v_add_f32_dpp v54, v7, v7 quad_perm:[2,3,0,1] row_mask:0xf bank_mask:0xf bound_ctrl:1
	v_add_f32_dpp v55, v4, v4 quad_perm:[2,3,0,1] row_mask:0xf bank_mask:0xf bound_ctrl:1
	ds_read_b128 v[4:7], v66 offset:8704
	ds_read_b128 v[20:23], v66 offset:16896
	ds_read_b128 v[24:27], v66 offset:25088
	ds_read_b128 v[28:31], v66 offset:512
	ds_read_b128 v[32:35], v66 offset:33280
	ds_read_b64 v[52:53], v65 offset:256
	v_add_f32_dpp v54, v54, v54 row_half_mirror row_mask:0xf bank_mask:0xf bound_ctrl:1
	v_add_f32_dpp v55, v55, v55 row_half_mirror row_mask:0xf bank_mask:0xf bound_ctrl:1
	v_add_u32_e32 v76, 0xc00, v67
	v_add_f32_dpp v54, v54, v54 row_mirror row_mask:0xf bank_mask:0xf bound_ctrl:1
	v_add_f32_dpp v70, v55, v55 row_mirror row_mask:0xf bank_mask:0xf bound_ctrl:1
	s_waitcnt lgkmcnt(10)
	v_pk_mul_f32 v[72:73], v[8:9], v[54:55] op_sel_hi:[1,0] neg_lo:[0,1] neg_hi:[0,1]
	v_pk_mul_f32 v[8:9], v[8:9], v[70:71] op_sel_hi:[1,0] neg_lo:[0,1] neg_hi:[0,1]
	v_pk_mul_f32 v[54:55], v[10:11], v[54:55] op_sel_hi:[1,0] neg_lo:[0,1] neg_hi:[0,1]
	v_pk_mul_f32 v[10:11], v[10:11], v[70:71] op_sel_hi:[1,0] neg_lo:[0,1] neg_hi:[0,1]
	s_waitcnt lgkmcnt(7)
	v_pk_fma_f32 v[70:71], v[40:41], v[0:1], v[72:73] op_sel_hi:[0,1,1]
	v_pk_fma_f32 v[0:1], v[40:41], v[0:1], v[8:9] op_sel:[1,0,0]
	v_pk_fma_f32 v[8:9], v[40:41], v[2:3], v[54:55] op_sel_hi:[0,1,1]
	v_pk_fma_f32 v[2:3], v[40:41], v[2:3], v[10:11] op_sel:[1,0,0]
	v_pk_fma_f32 v[40:41], v[42:43], v[12:13], v[0:1]
	v_pk_fma_f32 v[36:37], v[36:37], v[14:15], v[8:9]
	v_pk_fma_f32 v[42:43], v[46:47], v[14:15], v[2:3]
	v_pk_fma_f32 v[38:39], v[38:39], v[12:13], v[70:71]
	v_pk_mul_f32 v[0:1], v[18:19], v[36:37]
	v_pk_mul_f32 v[2:3], v[18:19], v[42:43]
	s_waitcnt lgkmcnt(4)
	v_pk_mul_f32 v[8:9], v[36:37], v[22:23]
	v_pk_mul_f32 v[10:11], v[42:43], v[22:23]
	v_pk_fma_f32 v[0:1], v[16:17], v[38:39], v[0:1]
	v_pk_fma_f32 v[2:3], v[16:17], v[40:41], v[2:3]
	v_pk_fma_f32 v[8:9], v[38:39], v[20:21], v[8:9]
	v_pk_fma_f32 v[10:11], v[40:41], v[20:21], v[10:11]
	v_add_f32_e32 v0, v0, v1
	v_add_f32_e32 v1, v2, v3
	v_add_f32_e32 v2, v8, v9
	v_add_f32_e32 v3, v10, v11
	v_add_f32_dpp v0, v0, v0 quad_perm:[1,0,3,2] row_mask:0xf bank_mask:0xf bound_ctrl:1
	v_add_f32_dpp v2, v2, v2 quad_perm:[1,0,3,2] row_mask:0xf bank_mask:0xf bound_ctrl:1
	v_add_f32_dpp v3, v3, v3 quad_perm:[1,0,3,2] row_mask:0xf bank_mask:0xf bound_ctrl:1
	v_add_f32_dpp v1, v1, v1 quad_perm:[1,0,3,2] row_mask:0xf bank_mask:0xf bound_ctrl:1
	v_add_f32_dpp v2, v2, v2 quad_perm:[2,3,0,1] row_mask:0xf bank_mask:0xf bound_ctrl:1
	v_add_f32_dpp v3, v3, v3 quad_perm:[2,3,0,1] row_mask:0xf bank_mask:0xf bound_ctrl:1
	v_add_f32_dpp v0, v0, v0 quad_perm:[2,3,0,1] row_mask:0xf bank_mask:0xf bound_ctrl:1
	v_add_f32_dpp v54, v2, v2 row_half_mirror row_mask:0xf bank_mask:0xf bound_ctrl:1
	v_add_f32_dpp v55, v3, v3 row_half_mirror row_mask:0xf bank_mask:0xf bound_ctrl:1
	v_add_f32_dpp v1, v1, v1 quad_perm:[2,3,0,1] row_mask:0xf bank_mask:0xf bound_ctrl:1
	v_add_f32_dpp v54, v54, v54 row_mirror row_mask:0xf bank_mask:0xf bound_ctrl:1
	v_add_f32_dpp v70, v55, v55 row_mirror row_mask:0xf bank_mask:0xf bound_ctrl:1
	s_waitcnt lgkmcnt(3)
	v_pk_mul_f32 v[72:73], v[24:25], v[54:55] op_sel_hi:[1,0] neg_lo:[0,1] neg_hi:[0,1]
	v_pk_mul_f32 v[24:25], v[24:25], v[70:71] op_sel_hi:[1,0] neg_lo:[0,1] neg_hi:[0,1]
	v_pk_mul_f32 v[54:55], v[26:27], v[54:55] op_sel_hi:[1,0] neg_lo:[0,1] neg_hi:[0,1]
	v_pk_mul_f32 v[26:27], v[26:27], v[70:71] op_sel_hi:[1,0] neg_lo:[0,1] neg_hi:[0,1]
	s_waitcnt lgkmcnt(0)
; template <int RPL, int NSW>
; __device__ __forceinline__ void scan_item(const P& p, LAS unsigned char* lds, int seqbase, int L, int head, int dir, int part, int step0, int nsteps, int mode, float* qc, float* smid) {
;     ...
;             for (int s = 0; s < TC; ++s) {
;                 const f32x2 w0 = {xw[0], xw[1]}, w1 = {xw[2], xw[3]}, kd0 = {xkd[0], xkd[1]}, kd1 = {xkd[2], xkd[3]}, kk0 = {xkk[0], xkk[1]}, kk1 = {xkk[2], xkk[3]},
;                             b0 = {xb[0], xb[1]}, b1 = {xb[2], xb[3]}, r0 = {xr[0], xr[1]}, r1 = {xr[2], xr[3]};
;                 float vr[RPL];
; #pragma unroll
;                 for (int q = 0; q < RPL; ++q) vr[q] = vrow[q];
;                 { const int sn = (s + 1 < TC) ? s + 1 : s; SCAN_LD(sn); }
;                 float sa[RPL];
; #pragma unroll
;                 for (int q = 0; q < RPL; ++q) { const f32x2 t = S[q][0] * kk0 + S[q][1] * kk1; sa[q] = t.x + t.y; }
;                 if (RPL == 2) {
;                     sa[0] += dppx<0xB1>(sa[0]); sa[RPL - 1] += dppx<0xB1>(sa[RPL - 1]); sa[0] += dppx<0x4E>(sa[0]); sa[RPL - 1] += dppx<0x4E>(sa[RPL - 1]);
;                     sa[0] += dppx<0x141>(sa[0]); sa[RPL - 1] += dppx<0x141>(sa[RPL - 1]); sa[0] += dppx<0x140>(sa[0]); sa[RPL - 1] += dppx<0x140>(sa[RPL - 1]);
;                 } else {
; #pragma unroll
;                     for (int q = 0; q < RPL; ++q) sa[q] = reduce16(sa[q]);
;                 }
;                 float ov[RPL];
;                 if (RPL == 2) {
;                     const f32x2 vva = {vr[0], vr[0]}, nsa = {-sa[0], -sa[0]}, vvb = {vr[RPL - 1], vr[RPL - 1]}, nsb = {-sa[RPL - 1], -sa[RPL - 1]};
;                     f32x2 a0 = nsa * b0, c0 = nsb * b0, a1 = nsa * b1, c1 = nsb * b1;
;                     a0 = vva * kd0 + a0; c0 = vvb * kd0 + c0; a1 = vva * kd1 + a1; c1 = vvb * kd1 + c1;
;                     S[0][0] = S[0][0] * w0 + a0; S[RPL - 1][0] = S[RPL - 1][0] * w0 + c0; S[0][1] = S[0][1] * w1 + a1; S[RPL - 1][1] = S[RPL - 1][1] * w1 + c1;
;                     f32x2 ua = S[0][0] * r0, ub = S[RPL - 1][0] * r0;
;                     ua = S[0][1] * r1 + ua; ub = S[RPL - 1][1] * r1 + ub;
;                     ov[0] = ua.x + ua.y; ov[RPL - 1] = ub.x + ub.y;
;                 } else {
; #pragma unroll
;                 for (int q = 0; q < RPL; ++q) {
;                     const f32x2 vv = {vr[q], vr[q]}, ns = {-sa[q], -sa[q]};
	v_pk_fma_f32 v[70:71], v[52:53], v[4:5], v[72:73] op_sel_hi:[0,1,1]
	v_pk_fma_f32 v[4:5], v[52:53], v[4:5], v[24:25] op_sel:[1,0,0]
	v_pk_fma_f32 v[24:25], v[52:53], v[6:7], v[54:55] op_sel_hi:[0,1,1]
	v_pk_fma_f32 v[6:7], v[52:53], v[6:7], v[26:27] op_sel:[1,0,0]
	ds_write2_b32 v74, v0, v1 offset1:4
	v_pk_fma_f32 v[36:37], v[36:37], v[30:31], v[24:25]
	v_pk_fma_f32 v[42:43], v[42:43], v[30:31], v[6:7]
	ds_read_b128 v[0:3], v66 offset:8960
	ds_read_b128 v[8:11], v66 offset:17152
	ds_read_b128 v[12:15], v66 offset:25344
	ds_read_b128 v[16:19], v66 offset:768
	ds_read_b128 v[20:23], v66 offset:33536
	ds_read_b64 v[46:47], v65 offset:384
	v_pk_fma_f32 v[38:39], v[38:39], v[28:29], v[70:71]
	v_pk_fma_f32 v[40:41], v[40:41], v[28:29], v[4:5]
	v_pk_mul_f32 v[4:5], v[34:35], v[36:37]
	v_pk_mul_f32 v[6:7], v[34:35], v[42:43]
	v_pk_fma_f32 v[4:5], v[32:33], v[38:39], v[4:5]
	v_pk_fma_f32 v[6:7], v[32:33], v[40:41], v[6:7]
	s_waitcnt lgkmcnt(4)
	v_pk_mul_f32 v[24:25], v[36:37], v[10:11]
	v_pk_mul_f32 v[10:11], v[42:43], v[10:11]
	v_add_f32_e32 v26, v4, v5
	v_add_f32_e32 v27, v6, v7
	v_pk_fma_f32 v[4:5], v[38:39], v[8:9], v[24:25]
	v_pk_fma_f32 v[6:7], v[40:41], v[8:9], v[10:11]
	v_add_f32_e32 v4, v4, v5
	v_add_f32_e32 v5, v6, v7
	v_add_f32_dpp v8, v26, v26 quad_perm:[1,0,3,2] row_mask:0xf bank_mask:0xf bound_ctrl:1
	v_add_f32_dpp v4, v4, v4 quad_perm:[1,0,3,2] row_mask:0xf bank_mask:0xf bound_ctrl:1
	v_add_f32_dpp v5, v5, v5 quad_perm:[1,0,3,2] row_mask:0xf bank_mask:0xf bound_ctrl:1
	v_add_f32_dpp v9, v27, v27 quad_perm:[1,0,3,2] row_mask:0xf bank_mask:0xf bound_ctrl:1
	v_add_f32_dpp v54, v4, v4 quad_perm:[2,3,0,1] row_mask:0xf bank_mask:0xf bound_ctrl:1
	v_add_f32_dpp v55, v5, v5 quad_perm:[2,3,0,1] row_mask:0xf bank_mask:0xf bound_ctrl:1
	v_add_f32_dpp v6, v8, v8 quad_perm:[2,3,0,1] row_mask:0xf bank_mask:0xf bound_ctrl:1
	v_add_f32_dpp v54, v54, v54 row_half_mirror row_mask:0xf bank_mask:0xf bound_ctrl:1
	v_add_f32_dpp v55, v55, v55 row_half_mirror row_mask:0xf bank_mask:0xf bound_ctrl:1
	v_add_f32_dpp v7, v9, v9 quad_perm:[2,3,0,1] row_mask:0xf bank_mask:0xf bound_ctrl:1
	v_add_f32_dpp v54, v54, v54 row_mirror row_mask:0xf bank_mask:0xf bound_ctrl:1
	v_add_f32_dpp v70, v55, v55 row_mirror row_mask:0xf bank_mask:0xf bound_ctrl:1
	s_waitcnt lgkmcnt(3)
	v_pk_mul_f32 v[72:73], v[12:13], v[54:55] op_sel_hi:[1,0] neg_lo:[0,1] neg_hi:[0,1]
	v_pk_mul_f32 v[12:13], v[12:13], v[70:71] op_sel_hi:[1,0] neg_lo:[0,1] neg_hi:[0,1]
	v_pk_mul_f32 v[54:55], v[14:15], v[54:55] op_sel_hi:[1,0] neg_lo:[0,1] neg_hi:[0,1]
	v_pk_mul_f32 v[14:15], v[14:15], v[70:71] op_sel_hi:[1,0] neg_lo:[0,1] neg_hi:[0,1]
	ds_write2_b32 v74, v6, v7 offset0:128 offset1:132
	s_waitcnt lgkmcnt(1)
	v_pk_fma_f32 v[70:71], v[46:47], v[0:1], v[72:73] op_sel_hi:[0,1,1]
	v_pk_fma_f32 v[0:1], v[46:47], v[0:1], v[12:13] op_sel:[1,0,0]
	v_pk_fma_f32 v[12:13], v[46:47], v[2:3], v[54:55] op_sel_hi:[0,1,1]
	v_pk_fma_f32 v[2:3], v[46:47], v[2:3], v[14:15] op_sel:[1,0,0]
	ds_read_b128 v[4:7], v66 offset:9216
	ds_read_b128 v[8:11], v66 offset:17408
	ds_read_b128 v[24:27], v66 offset:25600
	ds_read_b128 v[28:31], v66 offset:1024
	ds_read_b128 v[32:35], v66 offset:33792
	ds_read_b64 v[52:53], v65 offset:512
	v_pk_fma_f32 v[36:37], v[36:37], v[18:19], v[12:13]
	v_pk_fma_f32 v[42:43], v[42:43], v[18:19], v[2:3]
	v_pk_fma_f32 v[38:39], v[38:39], v[16:17], v[70:71]
	v_pk_fma_f32 v[40:41], v[40:41], v[16:17], v[0:1]
	v_pk_mul_f32 v[0:1], v[22:23], v[36:37]
	v_pk_mul_f32 v[2:3], v[22:23], v[42:43]
	s_waitcnt lgkmcnt(4)
	v_pk_mul_f32 v[12:13], v[36:37], v[10:11]
	v_pk_mul_f32 v[10:11], v[42:43], v[10:11]
	v_pk_fma_f32 v[0:1], v[20:21], v[38:39], v[0:1]
	v_pk_fma_f32 v[2:3], v[20:21], v[40:41], v[2:3]
	v_pk_fma_f32 v[12:13], v[38:39], v[8:9], v[12:13]
	v_pk_fma_f32 v[8:9], v[40:41], v[8:9], v[10:11]
	v_add_f32_e32 v0, v0, v1
	v_add_f32_e32 v1, v2, v3
	v_add_f32_e32 v2, v12, v13
	v_add_f32_e32 v3, v8, v9
	v_add_f32_dpp v0, v0, v0 quad_perm:[1,0,3,2] row_mask:0xf bank_mask:0xf bound_ctrl:1
	v_add_f32_dpp v2, v2, v2 quad_perm:[1,0,3,2] row_mask:0xf bank_mask:0xf bound_ctrl:1
	v_add_f32_dpp v3, v3, v3 quad_perm:[1,0,3,2] row_mask:0xf bank_mask:0xf bound_ctrl:1
	v_add_f32_dpp v1, v1, v1 quad_perm:[1,0,3,2] row_mask:0xf bank_mask:0xf bound_ctrl:1
	v_add_f32_dpp v2, v2, v2 quad_perm:[2,3,0,1] row_mask:0xf bank_mask:0xf bound_ctrl:1
	v_add_f32_dpp v3, v3, v3 quad_perm:[2,3,0,1] row_mask:0xf bank_mask:0xf bound_ctrl:1
	v_add_f32_dpp v0, v0, v0 quad_perm:[2,3,0,1] row_mask:0xf bank_mask:0xf bound_ctrl:1
	v_add_f32_dpp v54, v2, v2 row_half_mirror row_mask:0xf bank_mask:0xf bound_ctrl:1
	v_add_f32_dpp v55, v3, v3 row_half_mirror row_mask:0xf bank_mask:0xf bound_ctrl:1
	v_add_f32_dpp v1, v1, v1 quad_perm:[2,3,0,1] row_mask:0xf bank_mask:0xf bound_ctrl:1
	v_add_f32_dpp v54, v54, v54 row_mirror row_mask:0xf bank_mask:0xf bound_ctrl:1
	v_add_f32_dpp v70, v55, v55 row_mirror row_mask:0xf bank_mask:0xf bound_ctrl:1
	s_waitcnt lgkmcnt(3)
	v_pk_mul_f32 v[72:73], v[24:25], v[54:55] op_sel_hi:[1,0] neg_lo:[0,1] neg_hi:[0,1]
	v_pk_mul_f32 v[24:25], v[24:25], v[70:71] op_sel_hi:[1,0] neg_lo:[0,1] neg_hi:[0,1]
	v_pk_mul_f32 v[54:55], v[26:27], v[54:55] op_sel_hi:[1,0] neg_lo:[0,1] neg_hi:[0,1]
	v_pk_mul_f32 v[26:27], v[26:27], v[70:71] op_sel_hi:[1,0] neg_lo:[0,1] neg_hi:[0,1]
	s_waitcnt lgkmcnt(0)
; template <int RPL, int NSW>
; __device__ __forceinline__ void scan_item(const P& p, LAS unsigned char* lds, int seqbase, int L, int head, int dir, int part, int step0, int nsteps, int mode, float* qc, float* smid) {
;     ...
;             for (int s = 0; s < TC; ++s) {
;                 const f32x2 w0 = {xw[0], xw[1]}, w1 = {xw[2], xw[3]}, kd0 = {xkd[0], xkd[1]}, kd1 = {xkd[2], xkd[3]}, kk0 = {xkk[0], xkk[1]}, kk1 = {xkk[2], xkk[3]},
;                             b0 = {xb[0], xb[1]}, b1 = {xb[2], xb[3]}, r0 = {xr[0], xr[1]}, r1 = {xr[2], xr[3]};
;                 float vr[RPL];
; #pragma unroll
;                 for (int q = 0; q < RPL; ++q) vr[q] = vrow[q];
;                 { const int sn = (s + 1 < TC) ? s + 1 : s; SCAN_LD(sn); }
;                 float sa[RPL];
; #pragma unroll
;                 for (int q = 0; q < RPL; ++q) { const f32x2 t = S[q][0] * kk0 + S[q][1] * kk1; sa[q] = t.x + t.y; }
;                 if (RPL == 2) {
;                     sa[0] += dppx<0xB1>(sa[0]); sa[RPL - 1] += dppx<0xB1>(sa[RPL - 1]); sa[0] += dppx<0x4E>(sa[0]); sa[RPL - 1] += dppx<0x4E>(sa[RPL - 1]);
;                     sa[0] += dppx<0x141>(sa[0]); sa[RPL - 1] += dppx<0x141>(sa[RPL - 1]); sa[0] += dppx<0x140>(sa[0]); sa[RPL - 1] += dppx<0x140>(sa[RPL - 1]);
;                 } else {
; #pragma unroll
;                     for (int q = 0; q < RPL; ++q) sa[q] = reduce16(sa[q]);
;                 }
;                 float ov[RPL];
;                 if (RPL == 2) {
;                     const f32x2 vva = {vr[0], vr[0]}, nsa = {-sa[0], -sa[0]}, vvb = {vr[RPL - 1], vr[RPL - 1]}, nsb = {-sa[RPL - 1], -sa[RPL - 1]};
;                     f32x2 a0 = nsa * b0, c0 = nsb * b0, a1 = nsa * b1, c1 = nsb * b1;
;                     a0 = vva * kd0 + a0; c0 = vvb * kd0 + c0; a1 = vva * kd1 + a1; c1 = vvb * kd1 + c1;
;                     S[0][0] = S[0][0] * w0 + a0; S[RPL - 1][0] = S[RPL - 1][0] * w0 + c0; S[0][1] = S[0][1] * w1 + a1; S[RPL - 1][1] = S[RPL - 1][1] * w1 + c1;
;                     f32x2 ua = S[0][0] * r0, ub = S[RPL - 1][0] * r0;
;                     ua = S[0][1] * r1 + ua; ub = S[RPL - 1][1] * r1 + ub;
;                     ov[0] = ua.x + ua.y; ov[RPL - 1] = ub.x + ub.y;
;                 } else {
; #pragma unroll
;                 for (int q = 0; q < RPL; ++q) {
;                     const f32x2 vv = {vr[q], vr[q]}, ns = {-sa[q], -sa[q]};
	v_pk_fma_f32 v[70:71], v[52:53], v[4:5], v[72:73] op_sel_hi:[0,1,1]
	v_pk_fma_f32 v[4:5], v[52:53], v[4:5], v[24:25] op_sel:[1,0,0]
	v_pk_fma_f32 v[24:25], v[52:53], v[6:7], v[54:55] op_sel_hi:[0,1,1]
	v_pk_fma_f32 v[6:7], v[52:53], v[6:7], v[26:27] op_sel:[1,0,0]
	ds_write2_b32 v75, v0, v1 offset1:4
	v_pk_fma_f32 v[36:37], v[36:37], v[30:31], v[24:25]
	v_pk_fma_f32 v[42:43], v[42:43], v[30:31], v[6:7]
	ds_read_b128 v[0:3], v66 offset:9472
	ds_read_b128 v[8:11], v66 offset:17664
	ds_read_b128 v[12:15], v66 offset:25856
	ds_read_b128 v[16:19], v66 offset:1280
	ds_read_b128 v[20:23], v66 offset:34048
	ds_read_b64 v[46:47], v65 offset:640
	v_pk_fma_f32 v[38:39], v[38:39], v[28:29], v[70:71]
	v_pk_fma_f32 v[40:41], v[40:41], v[28:29], v[4:5]
	v_pk_mul_f32 v[4:5], v[34:35], v[36:37]
	v_pk_mul_f32 v[6:7], v[34:35], v[42:43]
	v_pk_fma_f32 v[4:5], v[32:33], v[38:39], v[4:5]
	v_pk_fma_f32 v[6:7], v[32:33], v[40:41], v[6:7]
	s_waitcnt lgkmcnt(4)
	v_pk_mul_f32 v[24:25], v[36:37], v[10:11]
	v_pk_mul_f32 v[10:11], v[42:43], v[10:11]
	v_add_f32_e32 v26, v4, v5
	v_add_f32_e32 v27, v6, v7
	v_pk_fma_f32 v[4:5], v[38:39], v[8:9], v[24:25]
	v_pk_fma_f32 v[6:7], v[40:41], v[8:9], v[10:11]
	v_add_f32_e32 v4, v4, v5
	v_add_f32_e32 v5, v6, v7
	v_add_f32_dpp v8, v26, v26 quad_perm:[1,0,3,2] row_mask:0xf bank_mask:0xf bound_ctrl:1
	v_add_f32_dpp v4, v4, v4 quad_perm:[1,0,3,2] row_mask:0xf bank_mask:0xf bound_ctrl:1
	v_add_f32_dpp v5, v5, v5 quad_perm:[1,0,3,2] row_mask:0xf bank_mask:0xf bound_ctrl:1
	v_add_f32_dpp v9, v27, v27 quad_perm:[1,0,3,2] row_mask:0xf bank_mask:0xf bound_ctrl:1
	v_add_f32_dpp v54, v4, v4 quad_perm:[2,3,0,1] row_mask:0xf bank_mask:0xf bound_ctrl:1
	v_add_f32_dpp v55, v5, v5 quad_perm:[2,3,0,1] row_mask:0xf bank_mask:0xf bound_ctrl:1
	v_add_f32_dpp v6, v8, v8 quad_perm:[2,3,0,1] row_mask:0xf bank_mask:0xf bound_ctrl:1
	v_add_f32_dpp v54, v54, v54 row_half_mirror row_mask:0xf bank_mask:0xf bound_ctrl:1
	v_add_f32_dpp v55, v55, v55 row_half_mirror row_mask:0xf bank_mask:0xf bound_ctrl:1
	v_add_f32_dpp v7, v9, v9 quad_perm:[2,3,0,1] row_mask:0xf bank_mask:0xf bound_ctrl:1
	v_add_f32_dpp v54, v54, v54 row_mirror row_mask:0xf bank_mask:0xf bound_ctrl:1
	v_add_f32_dpp v70, v55, v55 row_mirror row_mask:0xf bank_mask:0xf bound_ctrl:1
	s_waitcnt lgkmcnt(3)
	v_pk_mul_f32 v[72:73], v[12:13], v[54:55] op_sel_hi:[1,0] neg_lo:[0,1] neg_hi:[0,1]
	v_pk_mul_f32 v[12:13], v[12:13], v[70:71] op_sel_hi:[1,0] neg_lo:[0,1] neg_hi:[0,1]
	v_pk_mul_f32 v[54:55], v[14:15], v[54:55] op_sel_hi:[1,0] neg_lo:[0,1] neg_hi:[0,1]
	v_pk_mul_f32 v[14:15], v[14:15], v[70:71] op_sel_hi:[1,0] neg_lo:[0,1] neg_hi:[0,1]
	ds_write2_b32 v75, v6, v7 offset0:128 offset1:132
	s_waitcnt lgkmcnt(1)
	v_pk_fma_f32 v[70:71], v[46:47], v[0:1], v[72:73] op_sel_hi:[0,1,1]
	v_pk_fma_f32 v[0:1], v[46:47], v[0:1], v[12:13] op_sel:[1,0,0]
	v_pk_fma_f32 v[12:13], v[46:47], v[2:3], v[54:55] op_sel_hi:[0,1,1]
	v_pk_fma_f32 v[2:3], v[46:47], v[2:3], v[14:15] op_sel:[1,0,0]
	ds_read_b128 v[4:7], v66 offset:9728
	ds_read_b128 v[8:11], v66 offset:17920
	ds_read_b128 v[24:27], v66 offset:26112
	ds_read_b128 v[28:31], v66 offset:1536
	ds_read_b128 v[32:35], v66 offset:34304
	ds_read_b64 v[52:53], v65 offset:768
	v_pk_fma_f32 v[36:37], v[36:37], v[18:19], v[12:13]
	v_pk_fma_f32 v[42:43], v[42:43], v[18:19], v[2:3]
	v_pk_fma_f32 v[38:39], v[38:39], v[16:17], v[70:71]
	v_pk_fma_f32 v[40:41], v[40:41], v[16:17], v[0:1]
	v_pk_mul_f32 v[0:1], v[22:23], v[36:37]
	v_pk_mul_f32 v[2:3], v[22:23], v[42:43]
	s_waitcnt lgkmcnt(4)
	v_pk_mul_f32 v[12:13], v[36:37], v[10:11]
	v_pk_mul_f32 v[10:11], v[42:43], v[10:11]
	v_pk_fma_f32 v[0:1], v[20:21], v[38:39], v[0:1]
	v_pk_fma_f32 v[2:3], v[20:21], v[40:41], v[2:3]
	v_pk_fma_f32 v[12:13], v[38:39], v[8:9], v[12:13]
	v_pk_fma_f32 v[8:9], v[40:41], v[8:9], v[10:11]
	v_add_f32_e32 v0, v0, v1
	v_add_f32_e32 v1, v2, v3
	v_add_f32_e32 v2, v12, v13
	v_add_f32_e32 v3, v8, v9
	v_add_f32_dpp v0, v0, v0 quad_perm:[1,0,3,2] row_mask:0xf bank_mask:0xf bound_ctrl:1
	v_add_f32_dpp v2, v2, v2 quad_perm:[1,0,3,2] row_mask:0xf bank_mask:0xf bound_ctrl:1
	v_add_f32_dpp v3, v3, v3 quad_perm:[1,0,3,2] row_mask:0xf bank_mask:0xf bound_ctrl:1
	v_add_f32_dpp v1, v1, v1 quad_perm:[1,0,3,2] row_mask:0xf bank_mask:0xf bound_ctrl:1
	v_add_f32_dpp v2, v2, v2 quad_perm:[2,3,0,1] row_mask:0xf bank_mask:0xf bound_ctrl:1
	v_add_f32_dpp v3, v3, v3 quad_perm:[2,3,0,1] row_mask:0xf bank_mask:0xf bound_ctrl:1
	v_add_f32_dpp v0, v0, v0 quad_perm:[2,3,0,1] row_mask:0xf bank_mask:0xf bound_ctrl:1
	v_add_f32_dpp v54, v2, v2 row_half_mirror row_mask:0xf bank_mask:0xf bound_ctrl:1
	v_add_f32_dpp v55, v3, v3 row_half_mirror row_mask:0xf bank_mask:0xf bound_ctrl:1
	v_add_f32_dpp v1, v1, v1 quad_perm:[2,3,0,1] row_mask:0xf bank_mask:0xf bound_ctrl:1
	v_add_f32_dpp v54, v54, v54 row_mirror row_mask:0xf bank_mask:0xf bound_ctrl:1
	v_add_f32_dpp v70, v55, v55 row_mirror row_mask:0xf bank_mask:0xf bound_ctrl:1
	s_waitcnt lgkmcnt(3)
	v_pk_mul_f32 v[72:73], v[24:25], v[54:55] op_sel_hi:[1,0] neg_lo:[0,1] neg_hi:[0,1]
	v_pk_mul_f32 v[24:25], v[24:25], v[70:71] op_sel_hi:[1,0] neg_lo:[0,1] neg_hi:[0,1]
	v_pk_mul_f32 v[54:55], v[26:27], v[54:55] op_sel_hi:[1,0] neg_lo:[0,1] neg_hi:[0,1]
	v_pk_mul_f32 v[26:27], v[26:27], v[70:71] op_sel_hi:[1,0] neg_lo:[0,1] neg_hi:[0,1]
	s_waitcnt lgkmcnt(0)
; template <int RPL, int NSW>
; __device__ __forceinline__ void scan_item(const P& p, LAS unsigned char* lds, int seqbase, int L, int head, int dir, int part, int step0, int nsteps, int mode, float* qc, float* smid) {
;     ...
;             for (int s = 0; s < TC; ++s) {
;                 const f32x2 w0 = {xw[0], xw[1]}, w1 = {xw[2], xw[3]}, kd0 = {xkd[0], xkd[1]}, kd1 = {xkd[2], xkd[3]}, kk0 = {xkk[0], xkk[1]}, kk1 = {xkk[2], xkk[3]},
;                             b0 = {xb[0], xb[1]}, b1 = {xb[2], xb[3]}, r0 = {xr[0], xr[1]}, r1 = {xr[2], xr[3]};
;                 float vr[RPL];
; #pragma unroll
;                 for (int q = 0; q < RPL; ++q) vr[q] = vrow[q];
;                 { const int sn = (s + 1 < TC) ? s + 1 : s; SCAN_LD(sn); }
;                 float sa[RPL];
; #pragma unroll
;                 for (int q = 0; q < RPL; ++q) { const f32x2 t = S[q][0] * kk0 + S[q][1] * kk1; sa[q] = t.x + t.y; }
;                 if (RPL == 2) {
;                     sa[0] += dppx<0xB1>(sa[0]); sa[RPL - 1] += dppx<0xB1>(sa[RPL - 1]); sa[0] += dppx<0x4E>(sa[0]); sa[RPL - 1] += dppx<0x4E>(sa[RPL - 1]);
;                     sa[0] += dppx<0x141>(sa[0]); sa[RPL - 1] += dppx<0x141>(sa[RPL - 1]); sa[0] += dppx<0x140>(sa[0]); sa[RPL - 1] += dppx<0x140>(sa[RPL - 1]);
;                 } else {
; #pragma unroll
;                     for (int q = 0; q < RPL; ++q) sa[q] = reduce16(sa[q]);
;                 }
;                 float ov[RPL];
;                 if (RPL == 2) {
;                     const f32x2 vva = {vr[0], vr[0]}, nsa = {-sa[0], -sa[0]}, vvb = {vr[RPL - 1], vr[RPL - 1]}, nsb = {-sa[RPL - 1], -sa[RPL - 1]};
;                     f32x2 a0 = nsa * b0, c0 = nsb * b0, a1 = nsa * b1, c1 = nsb * b1;
;                     a0 = vva * kd0 + a0; c0 = vvb * kd0 + c0; a1 = vva * kd1 + a1; c1 = vvb * kd1 + c1;
;                     S[0][0] = S[0][0] * w0 + a0; S[RPL - 1][0] = S[RPL - 1][0] * w0 + c0; S[0][1] = S[0][1] * w1 + a1; S[RPL - 1][1] = S[RPL - 1][1] * w1 + c1;
;                     f32x2 ua = S[0][0] * r0, ub = S[RPL - 1][0] * r0;
;                     ua = S[0][1] * r1 + ua; ub = S[RPL - 1][1] * r1 + ub;
;                     ov[0] = ua.x + ua.y; ov[RPL - 1] = ub.x + ub.y;
;                 } else {
; #pragma unroll
;                 for (int q = 0; q < RPL; ++q) {
;                     const f32x2 vv = {vr[q], vr[q]}, ns = {-sa[q], -sa[q]};
	v_pk_fma_f32 v[70:71], v[52:53], v[4:5], v[72:73] op_sel_hi:[0,1,1]
	v_pk_fma_f32 v[4:5], v[52:53], v[4:5], v[24:25] op_sel:[1,0,0]
	v_pk_fma_f32 v[24:25], v[52:53], v[6:7], v[54:55] op_sel_hi:[0,1,1]
	v_pk_fma_f32 v[6:7], v[52:53], v[6:7], v[26:27] op_sel:[1,0,0]
	ds_write2_b32 v76, v0, v1 offset1:4
	v_pk_fma_f32 v[36:37], v[36:37], v[30:31], v[24:25]
	v_pk_fma_f32 v[42:43], v[42:43], v[30:31], v[6:7]
	ds_read_b128 v[0:3], v66 offset:9984
	ds_read_b128 v[8:11], v66 offset:18176
	ds_read_b128 v[12:15], v66 offset:26368
	ds_read_b128 v[16:19], v66 offset:1792
	ds_read_b128 v[20:23], v66 offset:34560
	ds_read_b64 v[46:47], v65 offset:896
	v_pk_fma_f32 v[38:39], v[38:39], v[28:29], v[70:71]
	v_pk_fma_f32 v[40:41], v[40:41], v[28:29], v[4:5]
	v_pk_mul_f32 v[4:5], v[34:35], v[36:37]
	v_pk_mul_f32 v[6:7], v[34:35], v[42:43]
	v_pk_fma_f32 v[4:5], v[32:33], v[38:39], v[4:5]
	v_pk_fma_f32 v[6:7], v[32:33], v[40:41], v[6:7]
	s_waitcnt lgkmcnt(4)
	v_pk_mul_f32 v[24:25], v[36:37], v[10:11]
	v_pk_mul_f32 v[10:11], v[42:43], v[10:11]
	v_add_f32_e32 v26, v4, v5
	v_add_f32_e32 v27, v6, v7
	v_pk_fma_f32 v[4:5], v[38:39], v[8:9], v[24:25]
	v_pk_fma_f32 v[6:7], v[40:41], v[8:9], v[10:11]
	v_add_f32_e32 v4, v4, v5
	v_add_f32_e32 v5, v6, v7
	v_add_f32_dpp v8, v26, v26 quad_perm:[1,0,3,2] row_mask:0xf bank_mask:0xf bound_ctrl:1
	v_add_f32_dpp v4, v4, v4 quad_perm:[1,0,3,2] row_mask:0xf bank_mask:0xf bound_ctrl:1
	v_add_f32_dpp v5, v5, v5 quad_perm:[1,0,3,2] row_mask:0xf bank_mask:0xf bound_ctrl:1
	v_add_f32_dpp v9, v27, v27 quad_perm:[1,0,3,2] row_mask:0xf bank_mask:0xf bound_ctrl:1
	v_add_f32_dpp v54, v4, v4 quad_perm:[2,3,0,1] row_mask:0xf bank_mask:0xf bound_ctrl:1
	v_add_f32_dpp v55, v5, v5 quad_perm:[2,3,0,1] row_mask:0xf bank_mask:0xf bound_ctrl:1
	v_add_f32_dpp v6, v8, v8 quad_perm:[2,3,0,1] row_mask:0xf bank_mask:0xf bound_ctrl:1
	v_add_f32_dpp v54, v54, v54 row_half_mirror row_mask:0xf bank_mask:0xf bound_ctrl:1
	v_add_f32_dpp v55, v55, v55 row_half_mirror row_mask:0xf bank_mask:0xf bound_ctrl:1
	v_add_f32_dpp v7, v9, v9 quad_perm:[2,3,0,1] row_mask:0xf bank_mask:0xf bound_ctrl:1
	v_add_f32_dpp v54, v54, v54 row_mirror row_mask:0xf bank_mask:0xf bound_ctrl:1
	v_add_f32_dpp v70, v55, v55 row_mirror row_mask:0xf bank_mask:0xf bound_ctrl:1
	s_waitcnt lgkmcnt(3)
	v_pk_mul_f32 v[72:73], v[12:13], v[54:55] op_sel_hi:[1,0] neg_lo:[0,1] neg_hi:[0,1]
	v_pk_mul_f32 v[12:13], v[12:13], v[70:71] op_sel_hi:[1,0] neg_lo:[0,1] neg_hi:[0,1]
	v_pk_mul_f32 v[54:55], v[14:15], v[54:55] op_sel_hi:[1,0] neg_lo:[0,1] neg_hi:[0,1]
	v_pk_mul_f32 v[14:15], v[14:15], v[70:71] op_sel_hi:[1,0] neg_lo:[0,1] neg_hi:[0,1]
	ds_write2_b32 v76, v6, v7 offset0:128 offset1:132
	s_waitcnt lgkmcnt(1)
	v_pk_fma_f32 v[70:71], v[46:47], v[0:1], v[72:73] op_sel_hi:[0,1,1]
	v_pk_fma_f32 v[0:1], v[46:47], v[0:1], v[12:13] op_sel:[1,0,0]
	v_pk_fma_f32 v[12:13], v[46:47], v[2:3], v[54:55] op_sel_hi:[0,1,1]
	v_pk_fma_f32 v[2:3], v[46:47], v[2:3], v[14:15] op_sel:[1,0,0]
	ds_read_b128 v[4:7], v66 offset:10240
	ds_read_b128 v[8:11], v66 offset:18432
	ds_read_b128 v[24:27], v66 offset:26624
	ds_read_b128 v[28:31], v66 offset:2048
	ds_read_b128 v[32:35], v66 offset:34816
	ds_read_b64 v[52:53], v65 offset:1024
	v_pk_fma_f32 v[36:37], v[36:37], v[18:19], v[12:13]
	v_pk_fma_f32 v[42:43], v[42:43], v[18:19], v[2:3]
	v_pk_fma_f32 v[38:39], v[38:39], v[16:17], v[70:71]
	v_pk_fma_f32 v[40:41], v[40:41], v[16:17], v[0:1]
	v_pk_mul_f32 v[0:1], v[22:23], v[36:37]
	v_pk_mul_f32 v[2:3], v[22:23], v[42:43]
	s_waitcnt lgkmcnt(4)
	v_pk_mul_f32 v[12:13], v[36:37], v[10:11]
	v_pk_mul_f32 v[10:11], v[42:43], v[10:11]
	v_pk_fma_f32 v[0:1], v[20:21], v[38:39], v[0:1]
	v_pk_fma_f32 v[2:3], v[20:21], v[40:41], v[2:3]
	v_pk_fma_f32 v[12:13], v[38:39], v[8:9], v[12:13]
	v_pk_fma_f32 v[8:9], v[40:41], v[8:9], v[10:11]
	v_add_f32_e32 v0, v0, v1
	v_add_f32_e32 v1, v2, v3
	v_add_f32_e32 v2, v12, v13
	v_add_f32_e32 v3, v8, v9
	v_add_f32_dpp v0, v0, v0 quad_perm:[1,0,3,2] row_mask:0xf bank_mask:0xf bound_ctrl:1
	v_add_f32_dpp v2, v2, v2 quad_perm:[1,0,3,2] row_mask:0xf bank_mask:0xf bound_ctrl:1
	v_add_f32_dpp v3, v3, v3 quad_perm:[1,0,3,2] row_mask:0xf bank_mask:0xf bound_ctrl:1
	v_add_f32_dpp v1, v1, v1 quad_perm:[1,0,3,2] row_mask:0xf bank_mask:0xf bound_ctrl:1
	v_add_f32_dpp v2, v2, v2 quad_perm:[2,3,0,1] row_mask:0xf bank_mask:0xf bound_ctrl:1
	v_add_f32_dpp v3, v3, v3 quad_perm:[2,3,0,1] row_mask:0xf bank_mask:0xf bound_ctrl:1
	v_add_u32_e32 v77, 0x1000, v67
	v_add_f32_dpp v54, v2, v2 row_half_mirror row_mask:0xf bank_mask:0xf bound_ctrl:1
	v_add_f32_dpp v55, v3, v3 row_half_mirror row_mask:0xf bank_mask:0xf bound_ctrl:1
	v_add_f32_dpp v0, v0, v0 quad_perm:[2,3,0,1] row_mask:0xf bank_mask:0xf bound_ctrl:1
	v_add_f32_dpp v54, v54, v54 row_mirror row_mask:0xf bank_mask:0xf bound_ctrl:1
	v_add_f32_dpp v70, v55, v55 row_mirror row_mask:0xf bank_mask:0xf bound_ctrl:1
	s_waitcnt lgkmcnt(3)
	v_pk_mul_f32 v[72:73], v[24:25], v[54:55] op_sel_hi:[1,0] neg_lo:[0,1] neg_hi:[0,1]
	v_pk_mul_f32 v[24:25], v[24:25], v[70:71] op_sel_hi:[1,0] neg_lo:[0,1] neg_hi:[0,1]
	v_pk_mul_f32 v[54:55], v[26:27], v[54:55] op_sel_hi:[1,0] neg_lo:[0,1] neg_hi:[0,1]
	v_pk_mul_f32 v[26:27], v[26:27], v[70:71] op_sel_hi:[1,0] neg_lo:[0,1] neg_hi:[0,1]
	v_add_f32_dpp v1, v1, v1 quad_perm:[2,3,0,1] row_mask:0xf bank_mask:0xf bound_ctrl:1
	s_waitcnt lgkmcnt(0)
; template <int RPL, int NSW>
; __device__ __forceinline__ void scan_item(const P& p, LAS unsigned char* lds, int seqbase, int L, int head, int dir, int part, int step0, int nsteps, int mode, float* qc, float* smid) {
;     ...
;             for (int s = 0; s < TC; ++s) {
;                 const f32x2 w0 = {xw[0], xw[1]}, w1 = {xw[2], xw[3]}, kd0 = {xkd[0], xkd[1]}, kd1 = {xkd[2], xkd[3]}, kk0 = {xkk[0], xkk[1]}, kk1 = {xkk[2], xkk[3]},
;                             b0 = {xb[0], xb[1]}, b1 = {xb[2], xb[3]}, r0 = {xr[0], xr[1]}, r1 = {xr[2], xr[3]};
;                 float vr[RPL];
; #pragma unroll
;                 for (int q = 0; q < RPL; ++q) vr[q] = vrow[q];
;                 { const int sn = (s + 1 < TC) ? s + 1 : s; SCAN_LD(sn); }
;                 float sa[RPL];
; #pragma unroll
;                 for (int q = 0; q < RPL; ++q) { const f32x2 t = S[q][0] * kk0 + S[q][1] * kk1; sa[q] = t.x + t.y; }
;                 if (RPL == 2) {
;                     sa[0] += dppx<0xB1>(sa[0]); sa[RPL - 1] += dppx<0xB1>(sa[RPL - 1]); sa[0] += dppx<0x4E>(sa[0]); sa[RPL - 1] += dppx<0x4E>(sa[RPL - 1]);
;                     sa[0] += dppx<0x141>(sa[0]); sa[RPL - 1] += dppx<0x141>(sa[RPL - 1]); sa[0] += dppx<0x140>(sa[0]); sa[RPL - 1] += dppx<0x140>(sa[RPL - 1]);
;                 } else {
; #pragma unroll
;                     for (int q = 0; q < RPL; ++q) sa[q] = reduce16(sa[q]);
;                 }
;                 float ov[RPL];
;                 if (RPL == 2) {
;                     const f32x2 vva = {vr[0], vr[0]}, nsa = {-sa[0], -sa[0]}, vvb = {vr[RPL - 1], vr[RPL - 1]}, nsb = {-sa[RPL - 1], -sa[RPL - 1]};
;                     f32x2 a0 = nsa * b0, c0 = nsb * b0, a1 = nsa * b1, c1 = nsb * b1;
;                     a0 = vva * kd0 + a0; c0 = vvb * kd0 + c0; a1 = vva * kd1 + a1; c1 = vvb * kd1 + c1;
;                     S[0][0] = S[0][0] * w0 + a0; S[RPL - 1][0] = S[RPL - 1][0] * w0 + c0; S[0][1] = S[0][1] * w1 + a1; S[RPL - 1][1] = S[RPL - 1][1] * w1 + c1;
;                     f32x2 ua = S[0][0] * r0, ub = S[RPL - 1][0] * r0;
;                     ua = S[0][1] * r1 + ua; ub = S[RPL - 1][1] * r1 + ub;
;                     ov[0] = ua.x + ua.y; ov[RPL - 1] = ub.x + ub.y;
;                 } else {
; #pragma unroll
;                 for (int q = 0; q < RPL; ++q) {
;                     const f32x2 vv = {vr[q], vr[q]}, ns = {-sa[q], -sa[q]};
	v_pk_fma_f32 v[70:71], v[52:53], v[4:5], v[72:73] op_sel_hi:[0,1,1]
	v_pk_fma_f32 v[4:5], v[52:53], v[4:5], v[24:25] op_sel:[1,0,0]
	v_pk_fma_f32 v[24:25], v[52:53], v[6:7], v[54:55] op_sel_hi:[0,1,1]
	v_pk_fma_f32 v[6:7], v[52:53], v[6:7], v[26:27] op_sel:[1,0,0]
	ds_write2_b32 v77, v0, v1 offset1:4
	v_pk_fma_f32 v[36:37], v[36:37], v[30:31], v[24:25]
	v_pk_fma_f32 v[42:43], v[42:43], v[30:31], v[6:7]
	ds_read_b128 v[0:3], v66 offset:10496
	ds_read_b128 v[8:11], v66 offset:18688
	ds_read_b128 v[12:15], v66 offset:26880
	ds_read_b128 v[16:19], v66 offset:2304
	ds_read_b128 v[20:23], v66 offset:35072
	ds_read_b64 v[46:47], v65 offset:1152
	v_pk_fma_f32 v[38:39], v[38:39], v[28:29], v[70:71]
	v_pk_fma_f32 v[40:41], v[40:41], v[28:29], v[4:5]
	v_pk_mul_f32 v[4:5], v[34:35], v[36:37]
	v_pk_mul_f32 v[6:7], v[34:35], v[42:43]
	v_pk_fma_f32 v[4:5], v[32:33], v[38:39], v[4:5]
	v_pk_fma_f32 v[6:7], v[32:33], v[40:41], v[6:7]
	s_waitcnt lgkmcnt(4)
	v_pk_mul_f32 v[24:25], v[36:37], v[10:11]
	v_pk_mul_f32 v[10:11], v[42:43], v[10:11]
	v_add_f32_e32 v26, v4, v5
	v_add_f32_e32 v27, v6, v7
	v_pk_fma_f32 v[4:5], v[38:39], v[8:9], v[24:25]
	v_pk_fma_f32 v[6:7], v[40:41], v[8:9], v[10:11]
	v_add_f32_e32 v4, v4, v5
	v_add_f32_e32 v5, v6, v7
	v_add_f32_dpp v8, v26, v26 quad_perm:[1,0,3,2] row_mask:0xf bank_mask:0xf bound_ctrl:1
	v_add_f32_dpp v4, v4, v4 quad_perm:[1,0,3,2] row_mask:0xf bank_mask:0xf bound_ctrl:1
	v_add_f32_dpp v5, v5, v5 quad_perm:[1,0,3,2] row_mask:0xf bank_mask:0xf bound_ctrl:1
	v_add_f32_dpp v9, v27, v27 quad_perm:[1,0,3,2] row_mask:0xf bank_mask:0xf bound_ctrl:1
	v_add_f32_dpp v54, v4, v4 quad_perm:[2,3,0,1] row_mask:0xf bank_mask:0xf bound_ctrl:1
	v_add_f32_dpp v55, v5, v5 quad_perm:[2,3,0,1] row_mask:0xf bank_mask:0xf bound_ctrl:1
	v_add_f32_dpp v6, v8, v8 quad_perm:[2,3,0,1] row_mask:0xf bank_mask:0xf bound_ctrl:1
	v_add_f32_dpp v54, v54, v54 row_half_mirror row_mask:0xf bank_mask:0xf bound_ctrl:1
	v_add_f32_dpp v55, v55, v55 row_half_mirror row_mask:0xf bank_mask:0xf bound_ctrl:1
	v_add_f32_dpp v7, v9, v9 quad_perm:[2,3,0,1] row_mask:0xf bank_mask:0xf bound_ctrl:1
	v_add_f32_dpp v54, v54, v54 row_mirror row_mask:0xf bank_mask:0xf bound_ctrl:1
	v_add_f32_dpp v70, v55, v55 row_mirror row_mask:0xf bank_mask:0xf bound_ctrl:1
	s_waitcnt lgkmcnt(3)
	v_pk_mul_f32 v[72:73], v[12:13], v[54:55] op_sel_hi:[1,0] neg_lo:[0,1] neg_hi:[0,1]
	v_pk_mul_f32 v[12:13], v[12:13], v[70:71] op_sel_hi:[1,0] neg_lo:[0,1] neg_hi:[0,1]
	v_pk_mul_f32 v[54:55], v[14:15], v[54:55] op_sel_hi:[1,0] neg_lo:[0,1] neg_hi:[0,1]
	v_pk_mul_f32 v[14:15], v[14:15], v[70:71] op_sel_hi:[1,0] neg_lo:[0,1] neg_hi:[0,1]
	ds_write2_b32 v77, v6, v7 offset0:128 offset1:132
	s_waitcnt lgkmcnt(1)
	v_pk_fma_f32 v[70:71], v[46:47], v[0:1], v[72:73] op_sel_hi:[0,1,1]
	v_pk_fma_f32 v[0:1], v[46:47], v[0:1], v[12:13] op_sel:[1,0,0]
	v_pk_fma_f32 v[12:13], v[46:47], v[2:3], v[54:55] op_sel_hi:[0,1,1]
	v_pk_fma_f32 v[2:3], v[46:47], v[2:3], v[14:15] op_sel:[1,0,0]
	ds_read_b128 v[4:7], v66 offset:10752
	ds_read_b128 v[8:11], v66 offset:18944
	ds_read_b128 v[24:27], v66 offset:27136
	ds_read_b128 v[28:31], v66 offset:2560
	ds_read_b128 v[32:35], v66 offset:35328
	ds_read_b64 v[52:53], v65 offset:1280
	v_pk_fma_f32 v[36:37], v[36:37], v[18:19], v[12:13]
	v_pk_fma_f32 v[42:43], v[42:43], v[18:19], v[2:3]
	v_pk_fma_f32 v[38:39], v[38:39], v[16:17], v[70:71]
	v_pk_fma_f32 v[40:41], v[40:41], v[16:17], v[0:1]
	v_pk_mul_f32 v[0:1], v[22:23], v[36:37]
	v_pk_mul_f32 v[2:3], v[22:23], v[42:43]
	s_waitcnt lgkmcnt(4)
	v_pk_mul_f32 v[12:13], v[36:37], v[10:11]
	v_pk_mul_f32 v[10:11], v[42:43], v[10:11]
	v_pk_fma_f32 v[0:1], v[20:21], v[38:39], v[0:1]
	v_pk_fma_f32 v[2:3], v[20:21], v[40:41], v[2:3]
	v_pk_fma_f32 v[12:13], v[38:39], v[8:9], v[12:13]
	v_pk_fma_f32 v[8:9], v[40:41], v[8:9], v[10:11]
	v_add_f32_e32 v0, v0, v1
	v_add_f32_e32 v1, v2, v3
	v_add_f32_e32 v2, v12, v13
	v_add_f32_e32 v3, v8, v9
	v_add_f32_dpp v0, v0, v0 quad_perm:[1,0,3,2] row_mask:0xf bank_mask:0xf bound_ctrl:1
	v_add_f32_dpp v2, v2, v2 quad_perm:[1,0,3,2] row_mask:0xf bank_mask:0xf bound_ctrl:1
	v_add_f32_dpp v3, v3, v3 quad_perm:[1,0,3,2] row_mask:0xf bank_mask:0xf bound_ctrl:1
	v_add_f32_dpp v1, v1, v1 quad_perm:[1,0,3,2] row_mask:0xf bank_mask:0xf bound_ctrl:1
	v_add_f32_dpp v2, v2, v2 quad_perm:[2,3,0,1] row_mask:0xf bank_mask:0xf bound_ctrl:1
	v_add_f32_dpp v3, v3, v3 quad_perm:[2,3,0,1] row_mask:0xf bank_mask:0xf bound_ctrl:1
	v_add_u32_e32 v45, 0x1400, v67
	v_add_f32_dpp v54, v2, v2 row_half_mirror row_mask:0xf bank_mask:0xf bound_ctrl:1
	v_add_f32_dpp v55, v3, v3 row_half_mirror row_mask:0xf bank_mask:0xf bound_ctrl:1
	v_add_f32_dpp v0, v0, v0 quad_perm:[2,3,0,1] row_mask:0xf bank_mask:0xf bound_ctrl:1
	v_add_f32_dpp v54, v54, v54 row_mirror row_mask:0xf bank_mask:0xf bound_ctrl:1
	v_add_f32_dpp v70, v55, v55 row_mirror row_mask:0xf bank_mask:0xf bound_ctrl:1
	s_waitcnt lgkmcnt(3)
	v_pk_mul_f32 v[72:73], v[24:25], v[54:55] op_sel_hi:[1,0] neg_lo:[0,1] neg_hi:[0,1]
	v_pk_mul_f32 v[24:25], v[24:25], v[70:71] op_sel_hi:[1,0] neg_lo:[0,1] neg_hi:[0,1]
	v_pk_mul_f32 v[54:55], v[26:27], v[54:55] op_sel_hi:[1,0] neg_lo:[0,1] neg_hi:[0,1]
	v_pk_mul_f32 v[26:27], v[26:27], v[70:71] op_sel_hi:[1,0] neg_lo:[0,1] neg_hi:[0,1]
	v_add_f32_dpp v1, v1, v1 quad_perm:[2,3,0,1] row_mask:0xf bank_mask:0xf bound_ctrl:1
	s_waitcnt lgkmcnt(0)
; template <int RPL, int NSW>
; __device__ __forceinline__ void scan_item(const P& p, LAS unsigned char* lds, int seqbase, int L, int head, int dir, int part, int step0, int nsteps, int mode, float* qc, float* smid) {
;     ...
;             for (int s = 0; s < TC; ++s) {
;                 const f32x2 w0 = {xw[0], xw[1]}, w1 = {xw[2], xw[3]}, kd0 = {xkd[0], xkd[1]}, kd1 = {xkd[2], xkd[3]}, kk0 = {xkk[0], xkk[1]}, kk1 = {xkk[2], xkk[3]},
;                             b0 = {xb[0], xb[1]}, b1 = {xb[2], xb[3]}, r0 = {xr[0], xr[1]}, r1 = {xr[2], xr[3]};
;                 float vr[RPL];
; #pragma unroll
;                 for (int q = 0; q < RPL; ++q) vr[q] = vrow[q];
;                 { const int sn = (s + 1 < TC) ? s + 1 : s; SCAN_LD(sn); }
;                 float sa[RPL];
; #pragma unroll
;                 for (int q = 0; q < RPL; ++q) { const f32x2 t = S[q][0] * kk0 + S[q][1] * kk1; sa[q] = t.x + t.y; }
;                 if (RPL == 2) {
;                     sa[0] += dppx<0xB1>(sa[0]); sa[RPL - 1] += dppx<0xB1>(sa[RPL - 1]); sa[0] += dppx<0x4E>(sa[0]); sa[RPL - 1] += dppx<0x4E>(sa[RPL - 1]);
;                     sa[0] += dppx<0x141>(sa[0]); sa[RPL - 1] += dppx<0x141>(sa[RPL - 1]); sa[0] += dppx<0x140>(sa[0]); sa[RPL - 1] += dppx<0x140>(sa[RPL - 1]);
;                 } else {
; #pragma unroll
;                     for (int q = 0; q < RPL; ++q) sa[q] = reduce16(sa[q]);
;                 }
;                 float ov[RPL];
;                 if (RPL == 2) {
;                     const f32x2 vva = {vr[0], vr[0]}, nsa = {-sa[0], -sa[0]}, vvb = {vr[RPL - 1], vr[RPL - 1]}, nsb = {-sa[RPL - 1], -sa[RPL - 1]};
;                     f32x2 a0 = nsa * b0, c0 = nsb * b0, a1 = nsa * b1, c1 = nsb * b1;
;                     a0 = vva * kd0 + a0; c0 = vvb * kd0 + c0; a1 = vva * kd1 + a1; c1 = vvb * kd1 + c1;
;                     S[0][0] = S[0][0] * w0 + a0; S[RPL - 1][0] = S[RPL - 1][0] * w0 + c0; S[0][1] = S[0][1] * w1 + a1; S[RPL - 1][1] = S[RPL - 1][1] * w1 + c1;
;                     f32x2 ua = S[0][0] * r0, ub = S[RPL - 1][0] * r0;
;                     ua = S[0][1] * r1 + ua; ub = S[RPL - 1][1] * r1 + ub;
;                     ov[0] = ua.x + ua.y; ov[RPL - 1] = ub.x + ub.y;
;                 } else {
; #pragma unroll
;                 for (int q = 0; q < RPL; ++q) {
;                     const f32x2 vv = {vr[q], vr[q]}, ns = {-sa[q], -sa[q]};
	v_pk_fma_f32 v[70:71], v[52:53], v[4:5], v[72:73] op_sel_hi:[0,1,1]
	v_pk_fma_f32 v[4:5], v[52:53], v[4:5], v[24:25] op_sel:[1,0,0]
	v_pk_fma_f32 v[24:25], v[52:53], v[6:7], v[54:55] op_sel_hi:[0,1,1]
	v_pk_fma_f32 v[6:7], v[52:53], v[6:7], v[26:27] op_sel:[1,0,0]
	ds_write2_b32 v45, v0, v1 offset1:4
	v_pk_fma_f32 v[36:37], v[36:37], v[30:31], v[24:25]
	v_pk_fma_f32 v[42:43], v[42:43], v[30:31], v[6:7]
	ds_read_b128 v[0:3], v66 offset:11008
	ds_read_b128 v[8:11], v66 offset:19200
	ds_read_b128 v[12:15], v66 offset:27392
	ds_read_b128 v[16:19], v66 offset:2816
	ds_read_b128 v[20:23], v66 offset:35584
	ds_read_b64 v[46:47], v65 offset:1408
	v_pk_fma_f32 v[38:39], v[38:39], v[28:29], v[70:71]
	v_pk_fma_f32 v[40:41], v[40:41], v[28:29], v[4:5]
	v_pk_mul_f32 v[4:5], v[34:35], v[36:37]
	v_pk_mul_f32 v[6:7], v[34:35], v[42:43]
	v_pk_fma_f32 v[4:5], v[32:33], v[38:39], v[4:5]
	v_pk_fma_f32 v[6:7], v[32:33], v[40:41], v[6:7]
	s_waitcnt lgkmcnt(4)
	v_pk_mul_f32 v[24:25], v[36:37], v[10:11]
	v_pk_mul_f32 v[10:11], v[42:43], v[10:11]
	v_add_f32_e32 v26, v4, v5
	v_add_f32_e32 v27, v6, v7
	v_pk_fma_f32 v[4:5], v[38:39], v[8:9], v[24:25]
	v_pk_fma_f32 v[6:7], v[40:41], v[8:9], v[10:11]
	v_add_f32_dpp v8, v26, v26 quad_perm:[1,0,3,2] row_mask:0xf bank_mask:0xf bound_ctrl:1
	v_add_f32_dpp v9, v27, v27 quad_perm:[1,0,3,2] row_mask:0xf bank_mask:0xf bound_ctrl:1
	v_add_f32_e32 v4, v4, v5
	v_add_f32_e32 v5, v6, v7
	v_add_f32_dpp v6, v8, v8 quad_perm:[2,3,0,1] row_mask:0xf bank_mask:0xf bound_ctrl:1
	v_add_f32_dpp v7, v9, v9 quad_perm:[2,3,0,1] row_mask:0xf bank_mask:0xf bound_ctrl:1
	v_add_f32_dpp v4, v4, v4 quad_perm:[1,0,3,2] row_mask:0xf bank_mask:0xf bound_ctrl:1
	v_add_f32_dpp v5, v5, v5 quad_perm:[1,0,3,2] row_mask:0xf bank_mask:0xf bound_ctrl:1
	ds_write2_b32 v45, v6, v7 offset0:128 offset1:132
	v_add_f32_dpp v45, v4, v4 quad_perm:[2,3,0,1] row_mask:0xf bank_mask:0xf bound_ctrl:1
	v_add_f32_dpp v54, v5, v5 quad_perm:[2,3,0,1] row_mask:0xf bank_mask:0xf bound_ctrl:1
	ds_read_b128 v[4:7], v66 offset:11264
	ds_read_b128 v[8:11], v66 offset:19456
	ds_read_b128 v[24:27], v66 offset:27648
	ds_read_b128 v[28:31], v66 offset:3072
	ds_read_b128 v[32:35], v66 offset:35840
	ds_read_b64 v[52:53], v65 offset:1536
	v_add_f32_dpp v45, v45, v45 row_half_mirror row_mask:0xf bank_mask:0xf bound_ctrl:1
	v_add_f32_dpp v55, v54, v54 row_half_mirror row_mask:0xf bank_mask:0xf bound_ctrl:1
	v_add_u32_e32 v44, 0x1800, v67
	v_add_f32_dpp v54, v45, v45 row_mirror row_mask:0xf bank_mask:0xf bound_ctrl:1
	v_add_f32_dpp v70, v55, v55 row_mirror row_mask:0xf bank_mask:0xf bound_ctrl:1
	s_waitcnt lgkmcnt(10)
	v_pk_mul_f32 v[72:73], v[12:13], v[54:55] op_sel_hi:[1,0] neg_lo:[0,1] neg_hi:[0,1]
	v_pk_mul_f32 v[12:13], v[12:13], v[70:71] op_sel_hi:[1,0] neg_lo:[0,1] neg_hi:[0,1]
	v_pk_mul_f32 v[54:55], v[14:15], v[54:55] op_sel_hi:[1,0] neg_lo:[0,1] neg_hi:[0,1]
	v_pk_mul_f32 v[14:15], v[14:15], v[70:71] op_sel_hi:[1,0] neg_lo:[0,1] neg_hi:[0,1]
	s_waitcnt lgkmcnt(7)
	v_pk_fma_f32 v[70:71], v[46:47], v[0:1], v[72:73] op_sel_hi:[0,1,1]
	v_pk_fma_f32 v[0:1], v[46:47], v[0:1], v[12:13] op_sel:[1,0,0]
	v_pk_fma_f32 v[12:13], v[46:47], v[2:3], v[54:55] op_sel_hi:[0,1,1]
	v_pk_fma_f32 v[2:3], v[46:47], v[2:3], v[14:15] op_sel:[1,0,0]
	v_pk_fma_f32 v[36:37], v[36:37], v[18:19], v[12:13]
	v_pk_fma_f32 v[42:43], v[42:43], v[18:19], v[2:3]
	v_pk_fma_f32 v[38:39], v[38:39], v[16:17], v[70:71]
	v_pk_fma_f32 v[40:41], v[40:41], v[16:17], v[0:1]
	v_pk_mul_f32 v[0:1], v[22:23], v[36:37]
	v_pk_mul_f32 v[2:3], v[22:23], v[42:43]
	s_waitcnt lgkmcnt(4)
	v_pk_mul_f32 v[12:13], v[36:37], v[10:11]
	v_pk_mul_f32 v[10:11], v[42:43], v[10:11]
	v_pk_fma_f32 v[0:1], v[20:21], v[38:39], v[0:1]
	v_pk_fma_f32 v[2:3], v[20:21], v[40:41], v[2:3]
	v_pk_fma_f32 v[12:13], v[38:39], v[8:9], v[12:13]
	v_pk_fma_f32 v[8:9], v[40:41], v[8:9], v[10:11]
	v_add_f32_e32 v0, v0, v1
	v_add_f32_e32 v1, v2, v3
	v_add_f32_e32 v2, v12, v13
	v_add_f32_e32 v3, v8, v9
	v_add_f32_dpp v0, v0, v0 quad_perm:[1,0,3,2] row_mask:0xf bank_mask:0xf bound_ctrl:1
	v_add_f32_dpp v2, v2, v2 quad_perm:[1,0,3,2] row_mask:0xf bank_mask:0xf bound_ctrl:1
	v_add_f32_dpp v3, v3, v3 quad_perm:[1,0,3,2] row_mask:0xf bank_mask:0xf bound_ctrl:1
	v_add_f32_dpp v1, v1, v1 quad_perm:[1,0,3,2] row_mask:0xf bank_mask:0xf bound_ctrl:1
	v_add_f32_dpp v2, v2, v2 quad_perm:[2,3,0,1] row_mask:0xf bank_mask:0xf bound_ctrl:1
	v_add_f32_dpp v3, v3, v3 quad_perm:[2,3,0,1] row_mask:0xf bank_mask:0xf bound_ctrl:1
	v_add_f32_dpp v0, v0, v0 quad_perm:[2,3,0,1] row_mask:0xf bank_mask:0xf bound_ctrl:1
	v_add_f32_dpp v45, v2, v2 row_half_mirror row_mask:0xf bank_mask:0xf bound_ctrl:1
	v_add_f32_dpp v55, v3, v3 row_half_mirror row_mask:0xf bank_mask:0xf bound_ctrl:1
	v_add_f32_dpp v1, v1, v1 quad_perm:[2,3,0,1] row_mask:0xf bank_mask:0xf bound_ctrl:1
	v_add_f32_dpp v54, v45, v45 row_mirror row_mask:0xf bank_mask:0xf bound_ctrl:1
	v_add_f32_dpp v70, v55, v55 row_mirror row_mask:0xf bank_mask:0xf bound_ctrl:1
	s_waitcnt lgkmcnt(3)
	v_pk_mul_f32 v[72:73], v[24:25], v[54:55] op_sel_hi:[1,0] neg_lo:[0,1] neg_hi:[0,1]
	v_pk_mul_f32 v[24:25], v[24:25], v[70:71] op_sel_hi:[1,0] neg_lo:[0,1] neg_hi:[0,1]
	v_pk_mul_f32 v[54:55], v[26:27], v[54:55] op_sel_hi:[1,0] neg_lo:[0,1] neg_hi:[0,1]
	v_pk_mul_f32 v[26:27], v[26:27], v[70:71] op_sel_hi:[1,0] neg_lo:[0,1] neg_hi:[0,1]
	s_waitcnt lgkmcnt(0)
; template <int RPL, int NSW>
; __device__ __forceinline__ void scan_item(const P& p, LAS unsigned char* lds, int seqbase, int L, int head, int dir, int part, int step0, int nsteps, int mode, float* qc, float* smid) {
;     ...
;             for (int s = 0; s < TC; ++s) {
;                 const f32x2 w0 = {xw[0], xw[1]}, w1 = {xw[2], xw[3]}, kd0 = {xkd[0], xkd[1]}, kd1 = {xkd[2], xkd[3]}, kk0 = {xkk[0], xkk[1]}, kk1 = {xkk[2], xkk[3]},
;                             b0 = {xb[0], xb[1]}, b1 = {xb[2], xb[3]}, r0 = {xr[0], xr[1]}, r1 = {xr[2], xr[3]};
;                 float vr[RPL];
; #pragma unroll
;                 for (int q = 0; q < RPL; ++q) vr[q] = vrow[q];
;                 { const int sn = (s + 1 < TC) ? s + 1 : s; SCAN_LD(sn); }
;                 float sa[RPL];
; #pragma unroll
;                 for (int q = 0; q < RPL; ++q) { const f32x2 t = S[q][0] * kk0 + S[q][1] * kk1; sa[q] = t.x + t.y; }
;                 if (RPL == 2) {
;                     sa[0] += dppx<0xB1>(sa[0]); sa[RPL - 1] += dppx<0xB1>(sa[RPL - 1]); sa[0] += dppx<0x4E>(sa[0]); sa[RPL - 1] += dppx<0x4E>(sa[RPL - 1]);
;                     sa[0] += dppx<0x141>(sa[0]); sa[RPL - 1] += dppx<0x141>(sa[RPL - 1]); sa[0] += dppx<0x140>(sa[0]); sa[RPL - 1] += dppx<0x140>(sa[RPL - 1]);
;                 } else {
; #pragma unroll
;                     for (int q = 0; q < RPL; ++q) sa[q] = reduce16(sa[q]);
;                 }
;                 float ov[RPL];
;                 if (RPL == 2) {
;                     const f32x2 vva = {vr[0], vr[0]}, nsa = {-sa[0], -sa[0]}, vvb = {vr[RPL - 1], vr[RPL - 1]}, nsb = {-sa[RPL - 1], -sa[RPL - 1]};
;                     f32x2 a0 = nsa * b0, c0 = nsb * b0, a1 = nsa * b1, c1 = nsb * b1;
;                     a0 = vva * kd0 + a0; c0 = vvb * kd0 + c0; a1 = vva * kd1 + a1; c1 = vvb * kd1 + c1;
;                     S[0][0] = S[0][0] * w0 + a0; S[RPL - 1][0] = S[RPL - 1][0] * w0 + c0; S[0][1] = S[0][1] * w1 + a1; S[RPL - 1][1] = S[RPL - 1][1] * w1 + c1;
;                     f32x2 ua = S[0][0] * r0, ub = S[RPL - 1][0] * r0;
;                     ua = S[0][1] * r1 + ua; ub = S[RPL - 1][1] * r1 + ub;
;                     ov[0] = ua.x + ua.y; ov[RPL - 1] = ub.x + ub.y;
;                 } else {
; #pragma unroll
;                 for (int q = 0; q < RPL; ++q) {
;                     const f32x2 vv = {vr[q], vr[q]}, ns = {-sa[q], -sa[q]};
	v_pk_fma_f32 v[70:71], v[52:53], v[4:5], v[72:73] op_sel_hi:[0,1,1]
	v_pk_fma_f32 v[4:5], v[52:53], v[4:5], v[24:25] op_sel:[1,0,0]
	v_pk_fma_f32 v[24:25], v[52:53], v[6:7], v[54:55] op_sel_hi:[0,1,1]
	v_pk_fma_f32 v[6:7], v[52:53], v[6:7], v[26:27] op_sel:[1,0,0]
	ds_write2_b32 v44, v0, v1 offset1:4
	v_pk_fma_f32 v[36:37], v[36:37], v[30:31], v[24:25]
	v_pk_fma_f32 v[42:43], v[42:43], v[30:31], v[6:7]
	ds_read_b128 v[0:3], v66 offset:11520
	ds_read_b128 v[8:11], v66 offset:19712
	ds_read_b128 v[12:15], v66 offset:27904
	ds_read_b128 v[16:19], v66 offset:3328
	ds_read_b128 v[20:23], v66 offset:36096
	ds_read_b64 v[46:47], v65 offset:1664
	v_pk_fma_f32 v[38:39], v[38:39], v[28:29], v[70:71]
	v_pk_fma_f32 v[40:41], v[40:41], v[28:29], v[4:5]
	v_pk_mul_f32 v[4:5], v[34:35], v[36:37]
	v_pk_mul_f32 v[6:7], v[34:35], v[42:43]
	v_pk_fma_f32 v[4:5], v[32:33], v[38:39], v[4:5]
	v_pk_fma_f32 v[6:7], v[32:33], v[40:41], v[6:7]
	s_waitcnt lgkmcnt(4)
	v_pk_mul_f32 v[24:25], v[36:37], v[10:11]
	v_pk_mul_f32 v[10:11], v[42:43], v[10:11]
	v_add_f32_e32 v26, v4, v5
	v_add_f32_e32 v27, v6, v7
	v_pk_fma_f32 v[4:5], v[38:39], v[8:9], v[24:25]
	v_pk_fma_f32 v[6:7], v[40:41], v[8:9], v[10:11]
	v_add_f32_dpp v8, v26, v26 quad_perm:[1,0,3,2] row_mask:0xf bank_mask:0xf bound_ctrl:1
	v_add_f32_dpp v9, v27, v27 quad_perm:[1,0,3,2] row_mask:0xf bank_mask:0xf bound_ctrl:1
	v_add_f32_e32 v4, v4, v5
	v_add_f32_e32 v5, v6, v7
	v_add_f32_dpp v6, v8, v8 quad_perm:[2,3,0,1] row_mask:0xf bank_mask:0xf bound_ctrl:1
	v_add_f32_dpp v7, v9, v9 quad_perm:[2,3,0,1] row_mask:0xf bank_mask:0xf bound_ctrl:1
	v_add_f32_dpp v4, v4, v4 quad_perm:[1,0,3,2] row_mask:0xf bank_mask:0xf bound_ctrl:1
	v_add_f32_dpp v5, v5, v5 quad_perm:[1,0,3,2] row_mask:0xf bank_mask:0xf bound_ctrl:1
	ds_write2_b32 v44, v6, v7 offset0:128 offset1:132
	v_add_f32_dpp v44, v4, v4 quad_perm:[2,3,0,1] row_mask:0xf bank_mask:0xf bound_ctrl:1
	v_add_f32_dpp v45, v5, v5 quad_perm:[2,3,0,1] row_mask:0xf bank_mask:0xf bound_ctrl:1
	ds_read_b128 v[4:7], v66 offset:11776
	ds_read_b128 v[8:11], v66 offset:19968
	ds_read_b128 v[24:27], v66 offset:28160
	ds_read_b128 v[28:31], v66 offset:3584
	ds_read_b128 v[32:35], v66 offset:36352
	ds_read_b64 v[54:55], v65 offset:1792
	v_add_f32_dpp v44, v44, v44 row_half_mirror row_mask:0xf bank_mask:0xf bound_ctrl:1
	v_add_f32_dpp v45, v45, v45 row_half_mirror row_mask:0xf bank_mask:0xf bound_ctrl:1
	s_cmpk_lg_i32 s7, 0x2000
	v_add_f32_dpp v44, v44, v44 row_mirror row_mask:0xf bank_mask:0xf bound_ctrl:1
	v_add_f32_dpp v52, v45, v45 row_mirror row_mask:0xf bank_mask:0xf bound_ctrl:1
	s_waitcnt lgkmcnt(10)
	v_pk_mul_f32 v[70:71], v[12:13], v[44:45] op_sel_hi:[1,0] neg_lo:[0,1] neg_hi:[0,1]
	v_pk_mul_f32 v[12:13], v[12:13], v[52:53] op_sel_hi:[1,0] neg_lo:[0,1] neg_hi:[0,1]
	v_pk_mul_f32 v[44:45], v[14:15], v[44:45] op_sel_hi:[1,0] neg_lo:[0,1] neg_hi:[0,1]
	v_pk_mul_f32 v[14:15], v[14:15], v[52:53] op_sel_hi:[1,0] neg_lo:[0,1] neg_hi:[0,1]
	s_waitcnt lgkmcnt(7)
	v_pk_fma_f32 v[52:53], v[46:47], v[0:1], v[70:71] op_sel_hi:[0,1,1]
	v_pk_fma_f32 v[0:1], v[46:47], v[0:1], v[12:13] op_sel:[1,0,0]
	v_pk_fma_f32 v[12:13], v[46:47], v[2:3], v[44:45] op_sel_hi:[0,1,1]
	v_pk_fma_f32 v[2:3], v[46:47], v[2:3], v[14:15] op_sel:[1,0,0]
	v_pk_fma_f32 v[36:37], v[36:37], v[18:19], v[12:13]
	v_pk_fma_f32 v[42:43], v[42:43], v[18:19], v[2:3]
	v_pk_fma_f32 v[38:39], v[38:39], v[16:17], v[52:53]
	v_pk_fma_f32 v[40:41], v[40:41], v[16:17], v[0:1]
	v_pk_mul_f32 v[0:1], v[22:23], v[36:37]
	v_pk_mul_f32 v[2:3], v[22:23], v[42:43]
	s_waitcnt lgkmcnt(4)
	v_pk_mul_f32 v[12:13], v[36:37], v[10:11]
	v_pk_mul_f32 v[10:11], v[42:43], v[10:11]
	v_pk_fma_f32 v[0:1], v[20:21], v[38:39], v[0:1]
	v_pk_fma_f32 v[2:3], v[20:21], v[40:41], v[2:3]
	v_pk_fma_f32 v[12:13], v[38:39], v[8:9], v[12:13]
	v_pk_fma_f32 v[8:9], v[40:41], v[8:9], v[10:11]
	v_add_f32_e32 v0, v0, v1
	v_add_f32_e32 v1, v2, v3
	v_add_f32_e32 v2, v12, v13
	v_add_f32_e32 v3, v8, v9
	v_add_f32_dpp v0, v0, v0 quad_perm:[1,0,3,2] row_mask:0xf bank_mask:0xf bound_ctrl:1
	v_add_f32_dpp v1, v1, v1 quad_perm:[1,0,3,2] row_mask:0xf bank_mask:0xf bound_ctrl:1
	v_add_f32_dpp v2, v2, v2 quad_perm:[1,0,3,2] row_mask:0xf bank_mask:0xf bound_ctrl:1
	v_add_f32_dpp v3, v3, v3 quad_perm:[1,0,3,2] row_mask:0xf bank_mask:0xf bound_ctrl:1
	v_add_u32_e32 v56, 0x1c00, v67
	s_cselect_b32 s13, s5, 31
	v_add_f32_dpp v0, v0, v0 quad_perm:[2,3,0,1] row_mask:0xf bank_mask:0xf bound_ctrl:1
	v_add_f32_dpp v1, v1, v1 quad_perm:[2,3,0,1] row_mask:0xf bank_mask:0xf bound_ctrl:1
	v_add_f32_dpp v2, v2, v2 quad_perm:[2,3,0,1] row_mask:0xf bank_mask:0xf bound_ctrl:1
	v_add_f32_dpp v3, v3, v3 quad_perm:[2,3,0,1] row_mask:0xf bank_mask:0xf bound_ctrl:1
	v_lshl_add_u32 v57, s13, 8, v62
	ds_write2_b32 v56, v0, v1 offset1:4
	v_add_f32_dpp v0, v2, v2 row_half_mirror row_mask:0xf bank_mask:0xf bound_ctrl:1
	v_add_f32_dpp v1, v3, v3 row_half_mirror row_mask:0xf bank_mask:0xf bound_ctrl:1
	v_lshl_add_u32 v68, s13, 7, v63
	ds_read_b128 v[16:19], v57 offset:8192
	ds_read_b128 v[44:47], v57 offset:16384
	ds_read_b128 v[12:15], v57
	ds_read_b128 v[8:11], v57 offset:32768
	ds_read_b128 v[20:23], v57 offset:24576
	ds_read_b64 v[52:53], v68 offset:40960
	v_add_f32_dpp v0, v0, v0 row_mirror row_mask:0xf bank_mask:0xf bound_ctrl:1
	v_add_f32_dpp v2, v1, v1 row_mirror row_mask:0xf bank_mask:0xf bound_ctrl:1
	s_waitcnt lgkmcnt(10)
	v_pk_mul_f32 v[68:69], v[24:25], v[0:1] op_sel_hi:[1,0] neg_lo:[0,1] neg_hi:[0,1]
	v_pk_mul_f32 v[24:25], v[24:25], v[2:3] op_sel_hi:[1,0] neg_lo:[0,1] neg_hi:[0,1]
	v_pk_mul_f32 v[0:1], v[26:27], v[0:1] op_sel_hi:[1,0] neg_lo:[0,1] neg_hi:[0,1]
	v_pk_mul_f32 v[2:3], v[26:27], v[2:3] op_sel_hi:[1,0] neg_lo:[0,1] neg_hi:[0,1]
	s_waitcnt lgkmcnt(7)
	v_pk_fma_f32 v[26:27], v[54:55], v[4:5], v[68:69] op_sel_hi:[0,1,1]
	v_pk_fma_f32 v[4:5], v[54:55], v[4:5], v[24:25] op_sel:[1,0,0]
	v_pk_fma_f32 v[24:25], v[54:55], v[6:7], v[0:1] op_sel_hi:[0,1,1]
	v_pk_fma_f32 v[6:7], v[54:55], v[6:7], v[2:3] op_sel:[1,0,0]
	v_pk_fma_f32 v[2:3], v[36:37], v[30:31], v[24:25]
	v_pk_fma_f32 v[6:7], v[42:43], v[30:31], v[6:7]
	v_pk_fma_f32 v[0:1], v[38:39], v[28:29], v[26:27]
	v_pk_fma_f32 v[4:5], v[40:41], v[28:29], v[4:5]
	v_pk_mul_f32 v[24:25], v[34:35], v[2:3]
	v_pk_mul_f32 v[26:27], v[34:35], v[6:7]
	v_pk_fma_f32 v[24:25], v[32:33], v[0:1], v[24:25]
	v_pk_fma_f32 v[26:27], v[32:33], v[4:5], v[26:27]
	v_add_f32_e32 v24, v24, v25
	v_add_f32_e32 v25, v26, v27
	s_addk_i32 s7, 0x2000
	s_add_i32 s5, s5, 16
	v_add_f32_dpp v24, v24, v24 quad_perm:[1,0,3,2] row_mask:0xf bank_mask:0xf bound_ctrl:1
	v_add_f32_dpp v25, v25, v25 quad_perm:[1,0,3,2] row_mask:0xf bank_mask:0xf bound_ctrl:1
	s_cmpk_eq_i32 s7, 0x4000
	v_add_u32_e32 v65, 0x800, v65
	v_add_u32_e32 v66, 0x1000, v66
	v_add_f32_dpp v24, v24, v24 quad_perm:[2,3,0,1] row_mask:0xf bank_mask:0xf bound_ctrl:1
	v_add_f32_dpp v25, v25, v25 quad_perm:[2,3,0,1] row_mask:0xf bank_mask:0xf bound_ctrl:1
	ds_write2_b32 v56, v24, v25 offset0:128 offset1:132
	s_cbranch_scc0 .LBB0_976
; template <int RPL, int NSW>
; __device__ __forceinline__ void scan_item(const P& p, LAS unsigned char* lds, int seqbase, int L, int head, int dir, int part, int step0, int nsteps, int mode, float* qc, float* smid) {
;     ...
;             __syncthreads();
;         }
;         if (smid) {
; #pragma unroll
;             for (int q = 0; q < RPL; ++q) { const f32x4 sv = {S[q][0].x, S[q][0].y, S[q][1].x, S[q][1].y}; *(f32x4*)(smid + (size_t)(rowbase + lr0 + q) * 64 + 4 * kq) = sv; } }
	s_add_i32 s4, s4, 1
	s_cmpk_eq_i32 s4, 0x100
	s_waitcnt lgkmcnt(0)
	s_barrier
	s_cbranch_scc0 .LBB0_975
	s_cmp_eq_u64 s[8:9], 0
	s_cbranch_scc1 .LBB0_980
	v_lshlrev_b32_e32 v168, 2, v49
	v_ashrrev_i32_e32 v51, 31, v50
	v_ashrrev_i32_e32 v49, 31, v48
	v_lshl_add_u64 v[8:9], s[8:9], 0, v[168:169]
	v_lshlrev_b64 v[10:11], 8, v[50:51]
	v_lshlrev_b64 v[12:13], 8, v[48:49]
	v_lshl_add_u64 v[10:11], v[8:9], 0, v[10:11]
	v_lshl_add_u64 v[8:9], v[8:9], 0, v[12:13]
	global_store_dwordx4 v[8:9], v[0:3], off
	global_store_dwordx4 v[10:11], v[4:7], off

; template <int RPL, int NSW>
; __device__ __forceinline__ void scan_item(const P& p, LAS unsigned char* lds, int seqbase, int L, int head, int dir, int part, int step0, int nsteps, int mode, float* qc, float* smid) {
;     ...
;     if (is_prod) {
;         const int pw = (NSW == 4) ? (wave - 4) : (((wave >> 2) << 1) | (wave & 1));
;         const int ptid = pw * 64 + lane, s = ptid >> 3, d0 = (ptid & 7) * 8, c = head * 64 + d0;
;         float mu[6][8], kk_k[8], k_a[8], r_kk[8];
; #pragma unroll
;         for (int e = 0; e < 8; ++e) { mu[0][e] = p.in[13][c + e]; mu[1][e] = p.in[13][1920 + c + e]; mu[2][e] = p.in[13][512 + c + e]; mu[3][e] = p.in[13][1920 + 512 + c + e];
;             mu[4][e] = p.in[13][1024 + c + e]; mu[5][e] = p.in[13][1920 + 1024 + c + e]; kk_k[e] = p.in[19][c + e]; k_a[e] = p.in[20][c + e]; r_kk[e] = p.in[21][c + e]; }
;         float* BSd = (float*)(ws + WS_BS) + (size_t)dir * T * 8;
;     ...
;         ScanRaw cur, nxt;
;         { const int t = dir ? (L - 1 - (step0 + s)) : (step0 + s); scan_load(cur, ZR + (size_t)(seqbase + t) * 1536 + c, WA + (size_t)(seqbase + t) * 2048 + dir * 512 + c, t > 0, t < L - 1); }
;         nxt = cur;
.LBB0_1014:
	s_or_b64 exec, exec, s[0:1]
	s_and_b64 s[0:1], s[6:7], exec
	s_cselect_b32 s0, 0, 0x3000000
	s_add_u32 s58, s84, s0
	s_addc_u32 s59, s85, 0
	s_ashr_i32 s37, s36, 31
	s_lshl_b64 s[0:1], s[36:37], 1
	s_add_u32 s0, s58, s0
	v_or_b32_e32 v72, v171, v204
	s_addc_u32 s1, s59, s1
	s_lshl_b32 s13, s39, 1
	v_lshlrev_b32_e32 v221, 6, v72
	s_add_u32 s0, s0, s13
	v_cndmask_b32_e64 v72, 0, 1, s[16:17]
	v_mov_b32_e32 v171, v169
	s_addc_u32 s1, s1, 0
	v_lshlrev_b32_e32 v74, 7, v72
	v_mov_b32_e32 v181, v47
	v_mov_b32_e32 v47, v45
	v_lshlrev_b64 v[72:73], 8, v[170:171]
	v_lshlrev_b32_e32 v45, 4, v204
	v_lshl_add_u64 v[178:179], s[0:1], 0, v[168:169]
	v_or3_b32 v45, v72, v74, v45
	s_lshl_b32 s0, s46, 8
	v_subrev_co_u32_e32 v72, vcc, s0, v45
	s_mov_b32 s4, 0
	s_nop 0
	v_subbrev_co_u32_e32 v73, vcc, 0, v73, vcc
	s_mov_b32 s5, 2
	v_lshlrev_b32_e32 v68, 2, v204
	v_mov_b32_e32 v180, v27
	v_mov_b32_e32 v27, v46
	v_mov_b32_e32 v46, v25
	v_sub_u32_e32 v25, 0, v170
	v_lshl_add_u64 v[182:183], s[28:29], 0, v[72:73]
	s_waitcnt lgkmcnt(0)
	s_barrier

; #define LAS __attribute__((address_space(3)))
; __device__ __forceinline__ void unpack8h(const u32x4 w, float* f) { f[0] = hlo(w.x); f[1] = hhi(w.x); f[2] = hlo(w.y); f[3] = hhi(w.y); f[4] = hlo(w.z); f[5] = hhi(w.z); f[6] = hlo(w.w); f[7] = hhi(w.w); }
; __device__ __forceinline__ float sum8(float v) { v += __shfl_xor(v, 1); v += __shfl_xor(v, 2); v += __shfl_xor(v, 4); return v; }
; template <int RPL, int NSW>
; __device__ __forceinline__ void scan_item(const P& p, LAS unsigned char* lds, int seqbase, int L, int head, int dir, int part, int step0, int nsteps, int mode, float* qc, float* smid) {
;     ...
;             if (ch < NC) {
;                 LAS float* b = lf + (ch & 1) * BUF_FLOATS;
;                 float r[8], k[8], v[8], w[8], a[8];
;                 shift8r(cur.r[0], cur.r[1], cur.r[2], mu[0], mu[1], r);
;                 shift8r(cur.k[0], cur.k[1], cur.k[2], mu[2], mu[3], k);
;                 shift8r(cur.v[0], cur.v[1], cur.v[2], mu[4], mu[5], v);
;                 unpack8h(cur.w, w); unpack8h(cur.a, a);
;                 float kk[8], ss = 0.f;
; #pragma unroll
;                 for (int e = 0; e < 8; ++e) { kk[e] = k[e] * kk_k[e]; ss += kk[e] * kk[e]; }
;                 ss = sum8(ss);
;                 const float inv = 1.0f / fmaxf(sqrtf(ss), 1e-12f);
;                 if (mode == 0 && part == 0) {
;                     float bsum = 0.f;
; #pragma unroll
;                     for (int e = 0; e < 8; ++e) bsum += r[e] * (k[e] * (1.f + (a[e] - 1.f) * k_a[e])) * r_kk[e];
;                     bsum = sum8(bsum);
;                     const int stepb = step0 + ch * TC + s; const int tb = dir ? (L - 1 - stepb) : stepb;
;                     if ((ptid & 7) == 0) BSd[(size_t)(seqbase + tb) * 8 + head] = bsum;
;                 }
;                 f32x4 o0, o1;
;                 LAS float* dst = b + s * 64 + d0;
; #pragma unroll
;                 for (int e = 0; e < 4; ++e) { o0[e] = w[e]; o1[e] = w[4 + e]; }
;                 *(LAS f32x4*)(dst) = o0; *(LAS f32x4*)(dst + 4) = o1;
; #pragma unroll
;                 for (int e = 0; e < 4; ++e) { o0[e] = k[e] * (1.f + (a[e] - 1.f) * k_a[e]); o1[e] = k[4 + e] * (1.f + (a[4 + e] - 1.f) * k_a[4 + e]); }
.LBB0_1023:
	s_waitcnt vmcnt(8)
	v_lshlrev_b32_e32 v160, 16, v124
	v_lshlrev_b32_e32 v185, 16, v140
	v_lshlrev_b32_e32 v184, 16, v128
	v_pk_add_f32 v[184:185], v[184:185], v[160:161] op_sel_hi:[1,0] neg_lo:[0,1] neg_hi:[0,1]
	v_lshlrev_b32_e32 v162, 16, v126
	v_pk_mul_f32 v[184:185], v[52:53], v[184:185]
	v_lshlrev_b32_e32 v161, 16, v142
	v_add_f32_e32 v160, v184, v160
	v_add_f32_e32 v196, v160, v185
	v_lshlrev_b32_e32 v160, 16, v130
	v_pk_add_f32 v[160:161], v[160:161], v[162:163] op_sel_hi:[1,0] neg_lo:[0,1] neg_hi:[0,1]
	v_and_b32_e32 v163, 0xffff0000, v130
	v_pk_mul_f32 v[160:161], v[174:175], v[160:161]
	v_and_b32_e32 v185, 0xffff0000, v142
	v_add_f32_e32 v160, v160, v162
	v_add_f32_e32 v192, v160, v161
	v_and_b32_e32 v161, 0xffff0000, v126
	v_and_b32_e32 v160, 0xffff0000, v124
	v_and_b32_e32 v162, 0xffff0000, v128
	v_and_b32_e32 v184, 0xffff0000, v140
	v_pk_add_f32 v[162:163], v[162:163], v[160:161] neg_lo:[0,1] neg_hi:[0,1]
	v_and_b32_e32 v126, 0xffff0000, v125
	v_pk_fma_f32 v[162:163], v[48:49], v[162:163], v[160:161]
	v_pk_add_f32 v[160:161], v[184:185], v[160:161] neg_lo:[0,1] neg_hi:[0,1]
	v_and_b32_e32 v124, 0xffff0000, v129
	v_pk_fma_f32 v[198:199], v[64:65], v[160:161], v[162:163]
	v_lshlrev_b32_e32 v161, 16, v127
	v_lshlrev_b32_e32 v160, 16, v125
	v_lshlrev_b32_e32 v163, 16, v131
	v_lshlrev_b32_e32 v162, 16, v129
	v_and_b32_e32 v127, 0xffff0000, v127
	v_and_b32_e32 v125, 0xffff0000, v131
	v_lshlrev_b32_e32 v185, 16, v143
	v_lshlrev_b32_e32 v184, 16, v141
	v_pk_add_f32 v[162:163], v[162:163], v[160:161] neg_lo:[0,1] neg_hi:[0,1]
	v_and_b32_e32 v129, 0xffff0000, v143
	v_and_b32_e32 v128, 0xffff0000, v141
	v_pk_add_f32 v[124:125], v[124:125], v[126:127] neg_lo:[0,1] neg_hi:[0,1]
	v_pk_fma_f32 v[162:163], v[54:55], v[162:163], v[160:161]
	v_pk_add_f32 v[160:161], v[184:185], v[160:161] neg_lo:[0,1] neg_hi:[0,1]
	v_pk_fma_f32 v[124:125], v[50:51], v[124:125], v[126:127]
	v_pk_add_f32 v[126:127], v[128:129], v[126:127] neg_lo:[0,1] neg_hi:[0,1]
	v_pk_fma_f32 v[200:201], v[70:71], v[160:161], v[162:163]
	v_pk_fma_f32 v[202:203], v[66:67], v[126:127], v[124:125]
	v_mov_b32_e32 v197, v198
	v_pk_mul_f32 v[140:141], v[60:61], v[196:197]
	v_mov_b32_e32 v126, v200
	v_mov_b32_e32 v127, v202
	v_pk_mul_f32 v[124:125], v[140:141], v[140:141]
	v_pk_mul_f32 v[142:143], v[62:63], v[126:127]
	v_mov_b32_e32 v193, v199
	v_pk_mul_f32 v[126:127], v[142:143], v[142:143]
	v_add_f32_e32 v124, v124, v125
	v_pk_mul_f32 v[186:187], v[56:57], v[192:193]
	v_add_f32_e32 v124, v126, v124
	v_pk_mul_f32 v[128:129], v[186:187], v[186:187]
	v_mov_b32_e32 v130, v201
	v_mov_b32_e32 v131, v203
	v_add_f32_e32 v124, v127, v124
	v_pk_mul_f32 v[188:189], v[58:59], v[130:131]
	v_add_f32_e32 v124, v128, v124
	v_pk_mul_f32 v[130:131], v[188:189], v[188:189]
	v_add_f32_e32 v124, v129, v124
	v_add_f32_e32 v124, v130, v124
	v_add_f32_e32 v124, v131, v124
	ds_bpermute_b32 v125, v212, v124
	s_waitcnt vmcnt(5)
	v_cvt_f32_f16_e32 v160, v114
	v_cvt_f32_f16_sdwa v185, v114 dst_sel:DWORD dst_unused:UNUSED_PAD src0_sel:WORD_1
	v_cvt_f32_f16_sdwa v184, v112 dst_sel:DWORD dst_unused:UNUSED_PAD src0_sel:WORD_1
	v_cvt_f32_f16_e32 v163, v115
	s_waitcnt lgkmcnt(0)
	v_add_f32_e32 v124, v124, v125
	ds_bpermute_b32 v125, v213, v124
	v_cvt_f32_f16_e32 v162, v113
	v_cvt_f32_f16_sdwa v115, v115 dst_sel:DWORD dst_unused:UNUSED_PAD src0_sel:WORD_1
	v_cvt_f32_f16_sdwa v114, v113 dst_sel:DWORD dst_unused:UNUSED_PAD src0_sel:WORD_1
	v_add_f32_e32 v128, -1.0, v160
	s_waitcnt lgkmcnt(0)
	v_add_f32_e32 v113, v124, v125
	ds_bpermute_b32 v129, v214, v113
	v_pk_add_f32 v[124:125], v[184:185], -1.0 op_sel_hi:[1,0]
	v_pk_add_f32 v[126:127], v[162:163], -1.0 op_sel_hi:[1,0]
	v_pk_add_f32 v[130:131], v[114:115], -1.0 op_sel_hi:[1,0]
	s_and_b64 vcc, exec, s[10:11]
	v_fma_f32 v161, v44, v128, 1.0
	v_pk_fma_f32 v[208:209], v[46:47], v[124:125], 1.0 op_sel_hi:[1,1,0]
	v_pk_fma_f32 v[206:207], v[26:27], v[126:127], 1.0 op_sel_hi:[1,1,0]
	v_pk_fma_f32 v[204:205], v[180:181], v[130:131], 1.0 op_sel_hi:[1,1,0]
	s_cbranch_vccnz .LBB0_1025
	v_mul_f32_e32 v128, v192, v161
	v_pk_mul_f32 v[190:191], v[198:199], v[208:209]
	v_pk_mul_f32 v[194:195], v[200:201], v[206:207]
	v_pk_mul_f32 v[130:131], v[202:203], v[204:205]
	s_mov_b64 s[0:1], 0
	s_branch .LBB0_1026
